# prep_item: dsa-q gain loads and k_pe loads issued together (fewer exposed global round trips per item)
# speedup vs baseline: 1.0022x; 1.0022x over previous
; DI int opaque_tid() { int t = threadIdx.x; asm volatile("" : "+v"(t)); return t; }
; DI void prep_item(const Params& p, int layer, int item, char* smem) {
;     ...
;   const int tid = opaque_tid(), lane = tid & 63, wave = __builtin_amdgcn_readfirstlane(tid >> 6), r = lane & 31, h = lane >> 5;
;   const int tg = (item >> 3) * 4 + wave, hd = item & 7;
;   const int token = tg * 32 + r, b = token >> 12, s = token & 4095;
;   u16 (*sWq)[264] = (u16 (*)[264])smem;
;   u16 (*sWk)[136] = (u16 (*)[136])smem;
;   {
;     const u16* src = WUQ + (size_t)(hd * 96) * 256;
; #pragma unroll
;     for (int i = 0; i < 12; ++i) {
;       const int idx = tid + 256 * i, row = idx >> 5, c = idx & 31;
;       *(uint4*)&sWq[row][c * 8] = *(const uint4*)(src + (size_t)row * 256 + c * 8);
;     }
;   }
;   __syncthreads();
.LBB0_348:
	s_and_b64 vcc, exec, s[0:1]
	s_cbranch_vccz .LBB0_357
	v_mov_b32_e32 v159, v128
	s_lshr_b32 s1, s59, 1
	v_readfirstlane_b32 s0, v159
	s_ashr_i32 s0, s0, 6
	s_and_b32 s1, s1, 0x1fc
	s_add_i32 s0, s0, s1
	s_and_b32 s1, s59, 7
	s_lshl_b32 s5, s0, 5
	s_mul_i32 s12, s1, 0xc000
	v_readlane_b32 s13, v255, 1
	s_add_u32 s12, s13, s12
	v_readlane_b32 s13, v255, 2
	v_lshlrev_b32_e32 v162, 4, v159
	v_ashrrev_i32_e32 v4, 5, v159
	s_addc_u32 s13, s13, 0
	v_and_b32_e32 v2, 0x1f0, v162
	s_waitcnt lgkmcnt(0)
	v_ashrrev_i32_e32 v5, 31, v4
	v_lshl_add_u64 v[8:9], s[12:13], 0, v[2:3]
	v_lshlrev_b64 v[6:7], 9, v[4:5]
	v_lshl_add_u64 v[6:7], v[8:9], 0, v[6:7]
	s_movk_i32 s14, 0x210
	v_mad_u64_u32 v[10:11], s[12:13], v4, s14, v[2:3]
	global_load_dwordx4 v[16:19], v[6:7], off
	v_add_u32_e32 v163, 0x100, v159
	v_add_u32_e32 v164, 0x200, v159
	v_add_u32_e32 v165, 0x300, v159
	v_add_u32_e32 v166, 0x400, v159
	v_add_u32_e32 v167, 0x500, v159
	v_add_u32_e32 v168, 0x600, v159
	v_add_u32_e32 v169, 0x700, v159
	v_add_u32_e32 v1, 0x800, v159
	v_and_b32_e32 v161, 31, v159
	v_or_b32_e32 v0, s5, v161
	v_and_b32_e32 v158, 63, v159
	v_cmp_gt_u32_e32 vcc, 32, v158
	v_bfe_u32 v170, v159, 5, 1
	v_lshlrev_b32_e32 v154, 4, v170
	v_mov_b32_e32 v155, v3
	s_mov_b32 s30, 0x800000
	v_mad_u32_u24 v173, v161, s14, v154
	v_ashrrev_i32_e32 v4, 5, v163
	v_ashrrev_i32_e32 v5, 31, v4
	v_lshlrev_b64 v[6:7], 9, v[4:5]
	v_lshl_add_u64 v[6:7], v[8:9], 0, v[6:7]
	global_load_dwordx4 v[20:23], v[6:7], off
	v_ashrrev_i32_e32 v4, 5, v164
	v_ashrrev_i32_e32 v5, 31, v4
	v_lshlrev_b64 v[6:7], 9, v[4:5]
	v_lshl_add_u64 v[6:7], v[8:9], 0, v[6:7]
	global_load_dwordx4 v[24:27], v[6:7], off
	v_ashrrev_i32_e32 v4, 5, v165
	v_ashrrev_i32_e32 v5, 31, v4
	v_lshlrev_b64 v[6:7], 9, v[4:5]
	v_lshl_add_u64 v[6:7], v[8:9], 0, v[6:7]
	global_load_dwordx4 v[28:31], v[6:7], off
	v_ashrrev_i32_e32 v4, 5, v166
	v_ashrrev_i32_e32 v5, 31, v4
	v_lshlrev_b64 v[6:7], 9, v[4:5]
	v_lshl_add_u64 v[6:7], v[8:9], 0, v[6:7]
	global_load_dwordx4 v[32:35], v[6:7], off
	v_ashrrev_i32_e32 v4, 5, v167
	v_ashrrev_i32_e32 v5, 31, v4
	v_lshlrev_b64 v[6:7], 9, v[4:5]
	v_lshl_add_u64 v[6:7], v[8:9], 0, v[6:7]
	global_load_dwordx4 v[36:39], v[6:7], off
	v_ashrrev_i32_e32 v4, 5, v168
	v_ashrrev_i32_e32 v5, 31, v4
	v_lshlrev_b64 v[6:7], 9, v[4:5]
	v_lshl_add_u64 v[6:7], v[8:9], 0, v[6:7]
	global_load_dwordx4 v[40:43], v[6:7], off
	v_ashrrev_i32_e32 v4, 5, v169
	v_ashrrev_i32_e32 v5, 31, v4
	v_lshlrev_b64 v[6:7], 9, v[4:5]
	v_lshl_add_u64 v[6:7], v[8:9], 0, v[6:7]
	global_load_dwordx4 v[44:47], v[6:7], off
	v_ashrrev_i32_e32 v4, 5, v1
	v_ashrrev_i32_e32 v5, 31, v4
	v_lshlrev_b64 v[6:7], 9, v[4:5]
	v_lshl_add_u64 v[6:7], v[8:9], 0, v[6:7]
	global_load_dwordx4 v[48:51], v[6:7], off
	v_add_u32_e32 v1, 0x900, v159
	v_ashrrev_i32_e32 v4, 5, v1
	v_ashrrev_i32_e32 v5, 31, v4
	v_lshlrev_b64 v[6:7], 9, v[4:5]
	v_lshl_add_u64 v[6:7], v[8:9], 0, v[6:7]
	global_load_dwordx4 v[52:55], v[6:7], off
	v_add_u32_e32 v1, 0xa00, v159
	v_ashrrev_i32_e32 v4, 5, v1
	v_ashrrev_i32_e32 v5, 31, v4
	v_lshlrev_b64 v[6:7], 9, v[4:5]
	v_lshl_add_u64 v[6:7], v[8:9], 0, v[6:7]
	global_load_dwordx4 v[56:59], v[6:7], off
	v_add_u32_e32 v1, 0xb00, v159
	v_ashrrev_i32_e32 v4, 5, v1
	v_ashrrev_i32_e32 v5, 31, v4
	v_lshlrev_b64 v[6:7], 9, v[4:5]
	v_lshl_add_u64 v[6:7], v[8:9], 0, v[6:7]
	global_load_dwordx4 v[60:63], v[6:7], off
	v_ashrrev_i32_e32 v1, 31, v0
	v_lshl_add_u64 v[112:113], v[0:1], 2, s[62:63]
	s_mov_b32 s12, 0x6dc9c883
	s_mov_b32 s13, 0x3fc45f30
	s_waitcnt vmcnt(11)
	ds_write_b128 v10, v[16:19]
	s_waitcnt vmcnt(10)
	ds_write_b128 v10, v[20:23] offset:4224
	s_waitcnt vmcnt(9)
	ds_write_b128 v10, v[24:27] offset:8448
	s_waitcnt vmcnt(8)
	ds_write_b128 v10, v[28:31] offset:12672
	s_waitcnt vmcnt(7)
	ds_write_b128 v10, v[32:35] offset:16896
	s_waitcnt vmcnt(6)
	ds_write_b128 v10, v[36:39] offset:21120
	s_waitcnt vmcnt(5)
	ds_write_b128 v10, v[40:43] offset:25344
	s_waitcnt vmcnt(4)
	ds_write_b128 v10, v[44:47] offset:29568
	s_waitcnt vmcnt(3)
	ds_write_b128 v10, v[48:51] offset:33792
	s_waitcnt vmcnt(2)
	ds_write_b128 v10, v[52:55] offset:38016
	s_waitcnt vmcnt(1)
	ds_write_b128 v10, v[56:59] offset:42240
	s_waitcnt vmcnt(0)
	ds_write_b128 v10, v[60:63] offset:46464
	s_waitcnt lgkmcnt(0)
	s_barrier
; DI float bflo(uint32_t u) { return __uint_as_float(u << 16); }
; DI float bfhi(uint32_t u) { return __uint_as_float(u & 0xffff0000u); }
; DI void prep_item(const Params& p, int layer, int item, char* smem) {
;     ...
;   u16* prow = PROJ + (size_t)token * LDP;
;   const float posf = (float)p.pos[token];
;   float cs[8], sn[8];
;   {
;     const float IF0[8] = {1.0f, 0.5623413251903491f, 0.31622776601683794f, 0.1778279410038923f, 0.01f, 0.005623413251903491f, 0.0031622776601683794f, 0.0017782794100389228f};
;     const float IF1[8] = {0.1f, 0.05623413251903491f, 0.03162277660168379f, 0.01778279410038923f, 0.001f, 0.0005623413251903491f, 0.00031622776601683794f, 0.00017782794100389227f};
; #pragma unroll
;     for (int reg = 0; reg < 8; ++reg) {
;       const float inv = h ? IF1[reg] : IF0[reg];
;       const float ang = posf * inv;
;       double rv = (double)ang * 0.15915494309189535;
;       rv -= rint(rv);
;       const float fr = (float)rv;
;       sn[reg] = __builtin_amdgcn_sinf(fr);
;       cs[reg] = __builtin_amdgcn_cosf(fr);
;     }
;   }
;   {
;     bf16x8 bq[16];
;     float ss = 0.f;
; #pragma unroll
;     for (int ks = 0; ks < 16; ++ks) {
;       uint4 u = *(const uint4*)(prow + O_CQ + ks * 16 + 8 * h);
;       bq[ks] = __builtin_bit_cast(bf16x8, u);
;       float f;
;       f = bflo(u.x); ss += f * f; f = bfhi(u.x); ss += f * f; f = bflo(u.y); ss += f * f; f = bfhi(u.y); ss += f * f;
;       f = bflo(u.z); ss += f * f; f = bfhi(u.z); ss += f * f; f = bflo(u.w); ss += f * f; f = bfhi(u.w); ss += f * f;
;     }
	global_load_dword v2, v[112:113], off
	v_mov_b32_e32 v4, 0x3dcccccd
	v_cndmask_b32_e64 v4, v4, 1.0, vcc
	s_waitcnt vmcnt(0)
	v_cvt_f32_i32_e32 v2, v2
	v_mul_f32_e32 v4, v4, v2
	v_cvt_f64_f32_e32 v[4:5], v4
	v_mul_f64 v[6:7], v[4:5], s[12:13]
	v_rndne_f64_e32 v[6:7], v[6:7]
	v_fma_f64 v[4:5], v[4:5], s[12:13], -v[6:7]
	v_cvt_f32_f64_e32 v4, v[4:5]
	v_sin_f32_e32 v116, v4
	v_cos_f32_e32 v118, v4
	v_mov_b32_e32 v4, 0x3d6655c3
	v_mov_b32_e32 v5, 0x3f0ff59a
	v_cndmask_b32_e32 v4, v4, v5, vcc
	v_mul_f32_e32 v4, v4, v2
	v_cvt_f64_f32_e32 v[4:5], v4
	v_mul_f64 v[6:7], v[4:5], s[12:13]
	v_rndne_f64_e32 v[6:7], v[6:7]
	v_fma_f64 v[4:5], v[4:5], s[12:13], -v[6:7]
	v_cvt_f32_f64_e32 v4, v[4:5]
	v_sin_f32_e32 v117, v4
	v_cos_f32_e32 v119, v4
	v_mov_b32_e32 v4, 0x3d0186e2
	v_mov_b32_e32 v5, 0x3ea1e89b
	v_cndmask_b32_e32 v4, v4, v5, vcc
	v_mul_f32_e32 v4, v4, v2
	v_cvt_f64_f32_e32 v[4:5], v4
	v_mul_f64 v[6:7], v[4:5], s[12:13]
	v_rndne_f64_e32 v[6:7], v[6:7]
	v_fma_f64 v[4:5], v[4:5], s[12:13], -v[6:7]
	v_cvt_f32_f64_e32 v4, v[4:5]
	v_sin_f32_e32 v120, v4
	v_cos_f32_e32 v122, v4
	v_mov_b32_e32 v4, 0x3c91ad39
	v_mov_b32_e32 v5, 0x3e361887
	v_cndmask_b32_e32 v4, v4, v5, vcc
	v_mul_f32_e32 v4, v4, v2
	v_cvt_f64_f32_e32 v[4:5], v4
	v_mul_f64 v[6:7], v[4:5], s[12:13]
	v_rndne_f64_e32 v[6:7], v[6:7]
	v_fma_f64 v[4:5], v[4:5], s[12:13], -v[6:7]
	v_cvt_f32_f64_e32 v4, v[4:5]
	v_sin_f32_e32 v121, v4
	v_cos_f32_e32 v123, v4
	v_mov_b32_e32 v4, 0x3a83126f
	v_cndmask_b32_e32 v4, v4, v219, vcc
	v_mul_f32_e32 v4, v4, v2
	v_cvt_f64_f32_e32 v[4:5], v4
	v_mul_f64 v[6:7], v[4:5], s[12:13]
	v_rndne_f64_e32 v[6:7], v[6:7]
	v_fma_f64 v[4:5], v[4:5], s[12:13], -v[6:7]
	v_cvt_f32_f64_e32 v4, v[4:5]
	v_sin_f32_e32 v124, v4
	v_cos_f32_e32 v126, v4
	v_cndmask_b32_e32 v4, v220, v221, vcc
	v_mul_f32_e32 v4, v4, v2
	v_cvt_f64_f32_e32 v[4:5], v4
	v_mul_f64 v[6:7], v[4:5], s[12:13]
	v_rndne_f64_e32 v[6:7], v[6:7]
	v_fma_f64 v[4:5], v[4:5], s[12:13], -v[6:7]
	v_cvt_f32_f64_e32 v4, v[4:5]
	v_sin_f32_e32 v125, v4
	v_cos_f32_e32 v127, v4
	v_cndmask_b32_e32 v4, v222, v223, vcc
	v_mul_f32_e32 v4, v4, v2
	v_cvt_f64_f32_e32 v[4:5], v4
	v_mul_f64 v[6:7], v[4:5], s[12:13]
	v_rndne_f64_e32 v[6:7], v[6:7]
	v_fma_f64 v[4:5], v[4:5], s[12:13], -v[6:7]
	v_cvt_f32_f64_e32 v4, v[4:5]
	v_sin_f32_e32 v150, v4
	v_cos_f32_e32 v152, v4
	v_cndmask_b32_e32 v4, v224, v135, vcc
	v_mul_f32_e32 v2, v4, v2
	v_cvt_f64_f32_e32 v[4:5], v2
	v_mul_f64 v[6:7], v[4:5], s[12:13]
	v_rndne_f64_e32 v[6:7], v[6:7]
	v_fma_f64 v[4:5], v[4:5], s[12:13], -v[6:7]
	v_readlane_b32 s12, v252, 32
	v_readlane_b32 s13, v252, 33
	v_cvt_f32_f64_e32 v2, v[4:5]
	v_sin_f32_e32 v151, v2
	v_mov_b64_e32 v[4:5], s[12:13]
	v_mad_i64_i32 v[114:115], s[12:13], v0, s54, v[4:5]
	v_lshl_add_u64 v[156:157], v[114:115], 0, v[154:155]
	global_load_dwordx4 v[4:7], v[156:157], off
	global_load_dwordx4 v[96:99], v[156:157], off offset:32
	global_load_dwordx4 v[100:103], v[156:157], off offset:64
	global_load_dwordx4 v[108:111], v[156:157], off offset:96
	global_load_dwordx4 v[104:107], v[156:157], off offset:128
	global_load_dwordx4 v[92:95], v[156:157], off offset:160
	global_load_dwordx4 v[88:91], v[156:157], off offset:192
	global_load_dwordx4 v[84:87], v[156:157], off offset:224
	global_load_dwordx4 v[80:83], v[156:157], off offset:256
	global_load_dwordx4 v[76:79], v[156:157], off offset:288
	global_load_dwordx4 v[72:75], v[156:157], off offset:320
	global_load_dwordx4 v[68:71], v[156:157], off offset:352
	global_load_dwordx4 v[64:67], v[156:157], off offset:384
	global_load_dwordx4 v[60:63], v[156:157], off offset:416
	global_load_dwordx4 v[56:59], v[156:157], off offset:448
	global_load_dwordx4 v[52:55], v[156:157], off offset:480
	v_cos_f32_e32 v153, v2
	v_lshlrev_b32_e32 v2, 3, v170
	s_waitcnt vmcnt(15)
	v_lshlrev_b32_e32 v8, 16, v4
	v_mul_f32_e32 v8, v8, v8
	v_and_b32_e32 v9, 0xffff0000, v4
	v_fmac_f32_e32 v8, v9, v9
	v_lshlrev_b32_e32 v9, 16, v5
	v_fmac_f32_e32 v8, v9, v9
	v_and_b32_e32 v9, 0xffff0000, v5
	v_fmac_f32_e32 v8, v9, v9
	v_lshlrev_b32_e32 v9, 16, v6
	v_fmac_f32_e32 v8, v9, v9
	v_and_b32_e32 v9, 0xffff0000, v6
	v_fmac_f32_e32 v8, v9, v9
	v_lshlrev_b32_e32 v9, 16, v7
	v_fmac_f32_e32 v8, v9, v9
	v_and_b32_e32 v9, 0xffff0000, v7
	v_fmac_f32_e32 v8, v9, v9
	s_waitcnt vmcnt(14)
	v_lshlrev_b32_e32 v9, 16, v96
	v_fmac_f32_e32 v8, v9, v9
	v_and_b32_e32 v9, 0xffff0000, v96
	v_fmac_f32_e32 v8, v9, v9
	v_lshlrev_b32_e32 v9, 16, v97
	v_fmac_f32_e32 v8, v9, v9
	v_and_b32_e32 v9, 0xffff0000, v97
	v_fmac_f32_e32 v8, v9, v9
	v_lshlrev_b32_e32 v9, 16, v98
	v_fmac_f32_e32 v8, v9, v9
	v_and_b32_e32 v9, 0xffff0000, v98
	v_fmac_f32_e32 v8, v9, v9
	v_lshlrev_b32_e32 v9, 16, v99
	v_fmac_f32_e32 v8, v9, v9
	v_and_b32_e32 v9, 0xffff0000, v99
	v_fmac_f32_e32 v8, v9, v9
	s_waitcnt vmcnt(13)
	v_lshlrev_b32_e32 v9, 16, v100
	v_fmac_f32_e32 v8, v9, v9
	v_and_b32_e32 v9, 0xffff0000, v100
	v_fmac_f32_e32 v8, v9, v9
	v_lshlrev_b32_e32 v9, 16, v101
	v_fmac_f32_e32 v8, v9, v9
	v_and_b32_e32 v9, 0xffff0000, v101
	v_fmac_f32_e32 v8, v9, v9
	v_lshlrev_b32_e32 v9, 16, v102
	v_fmac_f32_e32 v8, v9, v9
	v_and_b32_e32 v9, 0xffff0000, v102
	v_fmac_f32_e32 v8, v9, v9
	v_lshlrev_b32_e32 v9, 16, v103
	v_fmac_f32_e32 v8, v9, v9
	v_and_b32_e32 v9, 0xffff0000, v103
	v_fmac_f32_e32 v8, v9, v9
	s_waitcnt vmcnt(12)
	v_lshlrev_b32_e32 v9, 16, v108
	v_fmac_f32_e32 v8, v9, v9
	v_and_b32_e32 v9, 0xffff0000, v108
	v_fmac_f32_e32 v8, v9, v9
	v_lshlrev_b32_e32 v9, 16, v109
	v_fmac_f32_e32 v8, v9, v9
	v_and_b32_e32 v9, 0xffff0000, v109
	v_fmac_f32_e32 v8, v9, v9
	v_lshlrev_b32_e32 v9, 16, v110
	v_fmac_f32_e32 v8, v9, v9
	v_and_b32_e32 v9, 0xffff0000, v110
	v_fmac_f32_e32 v8, v9, v9
	v_lshlrev_b32_e32 v9, 16, v111
	v_fmac_f32_e32 v8, v9, v9
	v_and_b32_e32 v9, 0xffff0000, v111
	v_fmac_f32_e32 v8, v9, v9
	s_waitcnt vmcnt(11)
; DI float bflo(uint32_t u) { return __uint_as_float(u << 16); }
; DI float bfhi(uint32_t u) { return __uint_as_float(u & 0xffff0000u); }
; DI void prep_item(const Params& p, int layer, int item, char* smem) {
;     ...
;     for (int ks = 0; ks < 16; ++ks) {
;       uint4 u = *(const uint4*)(prow + O_CQ + ks * 16 + 8 * h);
;       bq[ks] = __builtin_bit_cast(bf16x8, u);
;       float f;
;       f = bflo(u.x); ss += f * f; f = bfhi(u.x); ss += f * f; f = bflo(u.y); ss += f * f; f = bfhi(u.y); ss += f * f;
;       f = bflo(u.z); ss += f * f; f = bfhi(u.z); ss += f * f; f = bflo(u.w); ss += f * f; f = bfhi(u.w); ss += f * f;
;     }
	v_lshlrev_b32_e32 v9, 16, v104
	v_fmac_f32_e32 v8, v9, v9
	v_and_b32_e32 v9, 0xffff0000, v104
	v_fmac_f32_e32 v8, v9, v9
	v_lshlrev_b32_e32 v9, 16, v105
	v_fmac_f32_e32 v8, v9, v9
	v_and_b32_e32 v9, 0xffff0000, v105
	v_fmac_f32_e32 v8, v9, v9
	v_lshlrev_b32_e32 v9, 16, v106
	v_fmac_f32_e32 v8, v9, v9
	v_and_b32_e32 v9, 0xffff0000, v106
	v_fmac_f32_e32 v8, v9, v9
	v_lshlrev_b32_e32 v9, 16, v107
	v_fmac_f32_e32 v8, v9, v9
	v_and_b32_e32 v9, 0xffff0000, v107
	v_fmac_f32_e32 v8, v9, v9
	s_waitcnt vmcnt(10)
	v_lshlrev_b32_e32 v9, 16, v92
	v_fmac_f32_e32 v8, v9, v9
	v_and_b32_e32 v9, 0xffff0000, v92
	v_fmac_f32_e32 v8, v9, v9
	v_lshlrev_b32_e32 v9, 16, v93
	v_fmac_f32_e32 v8, v9, v9
	v_and_b32_e32 v9, 0xffff0000, v93
	v_fmac_f32_e32 v8, v9, v9
	v_lshlrev_b32_e32 v9, 16, v94
	v_fmac_f32_e32 v8, v9, v9
	v_and_b32_e32 v9, 0xffff0000, v94
	v_fmac_f32_e32 v8, v9, v9
	v_lshlrev_b32_e32 v9, 16, v95
	v_fmac_f32_e32 v8, v9, v9
	v_and_b32_e32 v9, 0xffff0000, v95
	v_fmac_f32_e32 v8, v9, v9
	s_waitcnt vmcnt(9)
	v_lshlrev_b32_e32 v9, 16, v88
	v_fmac_f32_e32 v8, v9, v9
	v_and_b32_e32 v9, 0xffff0000, v88
	v_fmac_f32_e32 v8, v9, v9
	v_lshlrev_b32_e32 v9, 16, v89
	v_fmac_f32_e32 v8, v9, v9
	v_and_b32_e32 v9, 0xffff0000, v89
	v_fmac_f32_e32 v8, v9, v9
	v_lshlrev_b32_e32 v9, 16, v90
	v_fmac_f32_e32 v8, v9, v9
	v_and_b32_e32 v9, 0xffff0000, v90
	v_fmac_f32_e32 v8, v9, v9
	v_lshlrev_b32_e32 v9, 16, v91
	v_fmac_f32_e32 v8, v9, v9
	v_and_b32_e32 v9, 0xffff0000, v91
	v_fmac_f32_e32 v8, v9, v9
	s_waitcnt vmcnt(8)
	v_lshlrev_b32_e32 v9, 16, v84
	v_fmac_f32_e32 v8, v9, v9
	v_and_b32_e32 v9, 0xffff0000, v84
	v_fmac_f32_e32 v8, v9, v9
	v_lshlrev_b32_e32 v9, 16, v85
	v_fmac_f32_e32 v8, v9, v9
	v_and_b32_e32 v9, 0xffff0000, v85
	v_fmac_f32_e32 v8, v9, v9
	v_lshlrev_b32_e32 v9, 16, v86
	v_fmac_f32_e32 v8, v9, v9
	v_and_b32_e32 v9, 0xffff0000, v86
	v_fmac_f32_e32 v8, v9, v9
	v_lshlrev_b32_e32 v9, 16, v87
	v_fmac_f32_e32 v8, v9, v9
	v_and_b32_e32 v9, 0xffff0000, v87
	v_fmac_f32_e32 v8, v9, v9
	s_waitcnt vmcnt(7)
	v_lshlrev_b32_e32 v9, 16, v80
	v_fmac_f32_e32 v8, v9, v9
	v_and_b32_e32 v9, 0xffff0000, v80
	v_fmac_f32_e32 v8, v9, v9
	v_lshlrev_b32_e32 v9, 16, v81
	v_fmac_f32_e32 v8, v9, v9
	v_and_b32_e32 v9, 0xffff0000, v81
	v_fmac_f32_e32 v8, v9, v9
	v_lshlrev_b32_e32 v9, 16, v82
	v_fmac_f32_e32 v8, v9, v9
	v_and_b32_e32 v9, 0xffff0000, v82
	v_fmac_f32_e32 v8, v9, v9
	v_lshlrev_b32_e32 v9, 16, v83
	v_fmac_f32_e32 v8, v9, v9
	v_and_b32_e32 v9, 0xffff0000, v83
	v_fmac_f32_e32 v8, v9, v9
	s_waitcnt vmcnt(6)
	v_lshlrev_b32_e32 v9, 16, v76
	v_fmac_f32_e32 v8, v9, v9
	v_and_b32_e32 v9, 0xffff0000, v76
	v_fmac_f32_e32 v8, v9, v9
	v_lshlrev_b32_e32 v9, 16, v77
	v_fmac_f32_e32 v8, v9, v9
	v_and_b32_e32 v9, 0xffff0000, v77
	v_fmac_f32_e32 v8, v9, v9
	v_lshlrev_b32_e32 v9, 16, v78
	v_fmac_f32_e32 v8, v9, v9
	v_and_b32_e32 v9, 0xffff0000, v78
	v_fmac_f32_e32 v8, v9, v9
	v_lshlrev_b32_e32 v9, 16, v79
	v_fmac_f32_e32 v8, v9, v9
	v_and_b32_e32 v9, 0xffff0000, v79
	v_fmac_f32_e32 v8, v9, v9
	s_waitcnt vmcnt(5)
	v_lshlrev_b32_e32 v9, 16, v72
	v_fmac_f32_e32 v8, v9, v9
	v_and_b32_e32 v9, 0xffff0000, v72
	v_fmac_f32_e32 v8, v9, v9
	v_lshlrev_b32_e32 v9, 16, v73
	v_fmac_f32_e32 v8, v9, v9
	v_and_b32_e32 v9, 0xffff0000, v73
	v_fmac_f32_e32 v8, v9, v9
	v_lshlrev_b32_e32 v9, 16, v74
	v_fmac_f32_e32 v8, v9, v9
	v_and_b32_e32 v9, 0xffff0000, v74
	v_fmac_f32_e32 v8, v9, v9
	v_lshlrev_b32_e32 v9, 16, v75
	v_fmac_f32_e32 v8, v9, v9
	v_and_b32_e32 v9, 0xffff0000, v75
	v_fmac_f32_e32 v8, v9, v9
	s_waitcnt vmcnt(4)
	v_lshlrev_b32_e32 v9, 16, v68
	v_fmac_f32_e32 v8, v9, v9
	v_and_b32_e32 v9, 0xffff0000, v68
	v_fmac_f32_e32 v8, v9, v9
	v_lshlrev_b32_e32 v9, 16, v69
	v_fmac_f32_e32 v8, v9, v9
	v_and_b32_e32 v9, 0xffff0000, v69
	v_fmac_f32_e32 v8, v9, v9
	v_lshlrev_b32_e32 v9, 16, v70
	v_fmac_f32_e32 v8, v9, v9
	v_and_b32_e32 v9, 0xffff0000, v70
	v_fmac_f32_e32 v8, v9, v9
	v_lshlrev_b32_e32 v9, 16, v71
	v_fmac_f32_e32 v8, v9, v9
	v_and_b32_e32 v9, 0xffff0000, v71
	v_fmac_f32_e32 v8, v9, v9
	s_waitcnt vmcnt(3)
	v_lshlrev_b32_e32 v9, 16, v64
	v_fmac_f32_e32 v8, v9, v9
	v_and_b32_e32 v9, 0xffff0000, v64
	v_fmac_f32_e32 v8, v9, v9
	v_lshlrev_b32_e32 v9, 16, v65
	v_fmac_f32_e32 v8, v9, v9
	v_and_b32_e32 v9, 0xffff0000, v65
	v_fmac_f32_e32 v8, v9, v9
	v_lshlrev_b32_e32 v9, 16, v66
	v_fmac_f32_e32 v8, v9, v9
	v_and_b32_e32 v9, 0xffff0000, v66
	v_fmac_f32_e32 v8, v9, v9
	v_lshlrev_b32_e32 v9, 16, v67
	v_fmac_f32_e32 v8, v9, v9
	v_and_b32_e32 v9, 0xffff0000, v67
	v_fmac_f32_e32 v8, v9, v9
	s_waitcnt vmcnt(2)
	v_lshlrev_b32_e32 v9, 16, v60
	v_fmac_f32_e32 v8, v9, v9
	v_and_b32_e32 v9, 0xffff0000, v60
	v_fmac_f32_e32 v8, v9, v9
	v_lshlrev_b32_e32 v9, 16, v61
	v_fmac_f32_e32 v8, v9, v9
	v_and_b32_e32 v9, 0xffff0000, v61
	v_fmac_f32_e32 v8, v9, v9
	v_lshlrev_b32_e32 v9, 16, v62
	v_fmac_f32_e32 v8, v9, v9
	v_and_b32_e32 v9, 0xffff0000, v62
	v_fmac_f32_e32 v8, v9, v9
	v_lshlrev_b32_e32 v9, 16, v63
	v_fmac_f32_e32 v8, v9, v9
	v_and_b32_e32 v9, 0xffff0000, v63
	v_fmac_f32_e32 v8, v9, v9
	s_waitcnt vmcnt(1)
	v_lshlrev_b32_e32 v9, 16, v56
	v_fmac_f32_e32 v8, v9, v9
	v_and_b32_e32 v9, 0xffff0000, v56
	v_fmac_f32_e32 v8, v9, v9
	v_lshlrev_b32_e32 v9, 16, v57
	v_fmac_f32_e32 v8, v9, v9
	v_and_b32_e32 v9, 0xffff0000, v57
	v_fmac_f32_e32 v8, v9, v9
	v_lshlrev_b32_e32 v9, 16, v58
	v_fmac_f32_e32 v8, v9, v9
	v_and_b32_e32 v9, 0xffff0000, v58
	v_and_b32_e32 v10, 0xffff0000, v59
	v_lshlrev_b32_e32 v11, 16, v59
	v_fmac_f32_e32 v8, v9, v9
	v_pk_mul_f32 v[10:11], v[10:11], v[10:11]
	s_waitcnt vmcnt(0)
; #define MFMA32(a, b, c) __builtin_amdgcn_mfma_f32_32x32x16_bf16((a), (b), (c), 0, 0, 0)
; DI float xor32(float v) { return __shfl_xor(v, 32); }
; DI f32x16 zero16() { f32x16 z; _Pragma("unroll") for (int i = 0; i < 16; ++i) z[i] = 0.f; return z; }
; DI void prep_item(const Params& p, int layer, int item, char* smem) {
;     ...
;     ss += xor32(ss);
;     const float rq = rsqrtf(ss * (1.f / 256.f) + EPS);
;     f32x16 acc[3];
;     acc[0] = zero16(); acc[1] = zero16(); acc[2] = zero16();
; #pragma unroll
;     for (int ks = 0; ks < 16; ++ks) {
; #pragma unroll
;       for (int nt = 0; nt < 3; ++nt) {
;         bf16x8 a = *(const bf16x8*)&sWq[nt * 32 + r][ks * 16 + 8 * h];
;         acc[nt] = MFMA32(a, bq[ks], acc[nt]);
;       }
;     }
	v_lshlrev_b32_e32 v9, 16, v52
	v_add_f32_e32 v8, v11, v8
	v_add_f32_e32 v10, v10, v8
	v_and_b32_e32 v8, 0xffff0000, v52
	v_pk_mul_f32 v[8:9], v[8:9], v[8:9]
	s_nop 0
	v_add_f32_e32 v9, v9, v10
	v_add_f32_e32 v10, v8, v9
	v_and_b32_e32 v8, 0xffff0000, v53
	v_lshlrev_b32_e32 v9, 16, v53
	v_pk_mul_f32 v[8:9], v[8:9], v[8:9]
	s_nop 0
	v_add_f32_e32 v9, v9, v10
	v_add_f32_e32 v10, v8, v9
	v_and_b32_e32 v8, 0xffff0000, v54
	v_lshlrev_b32_e32 v9, 16, v54
	v_pk_mul_f32 v[8:9], v[8:9], v[8:9]
	s_nop 0
	v_add_f32_e32 v9, v9, v10
	v_add_f32_e32 v10, v8, v9
	v_and_b32_e32 v8, 0xffff0000, v55
	v_lshlrev_b32_e32 v9, 16, v55
	v_pk_mul_f32 v[8:9], v[8:9], v[8:9]
	s_nop 0
	v_add_f32_e32 v9, v9, v10
	v_and_b32_e32 v10, 64, v213
	v_add_f32_e32 v8, v8, v9
	v_xor_b32_e32 v9, 32, v213
	v_add_u32_e32 v160, 64, v10
	v_cmp_lt_i32_e32 vcc, v9, v160
	s_nop 1
	v_cndmask_b32_e32 v9, v213, v9, vcc
	v_lshlrev_b32_e32 v155, 2, v9
	ds_bpermute_b32 v9, v155, v8
	s_waitcnt lgkmcnt(0)
	v_add_f32_e32 v8, v8, v9
	v_fmamk_f32 v8, v8, 0x3b800000, v206
	v_cmp_gt_f32_e32 vcc, s30, v8
	v_mul_f32_e32 v9, 0x4b800000, v8
	s_nop 0
	v_cndmask_b32_e32 v8, v8, v9, vcc
	v_rsq_f32_e32 v171, v8
	ds_read_b128 v[8:11], v173
	ds_read_b128 v[174:177], v173 offset:32
	s_waitcnt lgkmcnt(1)
	v_mfma_f32_32x32x16_bf16 v[36:51], v[8:11], v[4:7], 0
	ds_read_b128 v[8:11], v173 offset:16896
	v_mul_f32_e32 v172, 0x45800000, v171
	s_waitcnt lgkmcnt(1)
	v_mfma_f32_32x32x16_bf16 v[36:51], v[174:177], v[96:99], v[36:51]
	ds_read_b128 v[174:177], v173 offset:16928
	s_waitcnt lgkmcnt(1)
	v_mfma_f32_32x32x16_bf16 v[20:35], v[8:11], v[4:7], 0
	ds_read_b128 v[8:11], v173 offset:33792
	s_waitcnt lgkmcnt(1)
	v_mfma_f32_32x32x16_bf16 v[20:35], v[174:177], v[96:99], v[20:35]
	ds_read_b128 v[174:177], v173 offset:33824
	s_waitcnt lgkmcnt(1)
	v_mfma_f32_32x32x16_bf16 v[4:19], v[8:11], v[4:7], 0
	s_waitcnt lgkmcnt(0)
	v_mfma_f32_32x32x16_bf16 v[4:19], v[174:177], v[96:99], v[4:19]
	ds_read_b128 v[96:99], v173 offset:64
	s_waitcnt lgkmcnt(0)
	v_mfma_f32_32x32x16_bf16 v[36:51], v[96:99], v[100:103], v[36:51]
	ds_read_b128 v[96:99], v173 offset:16960
	s_waitcnt lgkmcnt(0)
	v_mfma_f32_32x32x16_bf16 v[20:35], v[96:99], v[100:103], v[20:35]
	ds_read_b128 v[96:99], v173 offset:33856
	s_waitcnt lgkmcnt(0)
	v_mfma_f32_32x32x16_bf16 v[4:19], v[96:99], v[100:103], v[4:19]
	ds_read_b128 v[96:99], v173 offset:96
	s_waitcnt lgkmcnt(0)
	v_mfma_f32_32x32x16_bf16 v[36:51], v[96:99], v[108:111], v[36:51]
	ds_read_b128 v[96:99], v173 offset:16992
	s_waitcnt lgkmcnt(0)
	v_mfma_f32_32x32x16_bf16 v[20:35], v[96:99], v[108:111], v[20:35]
	ds_read_b128 v[96:99], v173 offset:33888
	s_waitcnt lgkmcnt(0)
	v_mfma_f32_32x32x16_bf16 v[4:19], v[96:99], v[108:111], v[4:19]
	ds_read_b128 v[96:99], v173 offset:128
	s_waitcnt lgkmcnt(0)
	v_mfma_f32_32x32x16_bf16 v[36:51], v[96:99], v[104:107], v[36:51]
	ds_read_b128 v[96:99], v173 offset:17024
	s_waitcnt lgkmcnt(0)
	v_mfma_f32_32x32x16_bf16 v[20:35], v[96:99], v[104:107], v[20:35]
	ds_read_b128 v[96:99], v173 offset:33920
	s_waitcnt lgkmcnt(0)
	v_mfma_f32_32x32x16_bf16 v[4:19], v[96:99], v[104:107], v[4:19]
	ds_read_b128 v[96:99], v173 offset:160
	s_waitcnt lgkmcnt(0)
	v_mfma_f32_32x32x16_bf16 v[36:51], v[96:99], v[92:95], v[36:51]
	ds_read_b128 v[96:99], v173 offset:17056
	s_waitcnt lgkmcnt(0)
	v_mfma_f32_32x32x16_bf16 v[20:35], v[96:99], v[92:95], v[20:35]
	ds_read_b128 v[96:99], v173 offset:33952
	s_waitcnt lgkmcnt(0)
	v_mfma_f32_32x32x16_bf16 v[4:19], v[96:99], v[92:95], v[4:19]
	ds_read_b128 v[92:95], v173 offset:192
	v_bitop3_b32 v97, s5, v225, v161 bitop3:0xc8
	s_ashr_i32 s5, s0, 4
	s_and_b32 s5, s5, -8
	s_or_b32 s12, s5, s1
	s_ashr_i32 s13, s12, 31
	s_lshl_b64 s[14:15], s[12:13], 12
	s_waitcnt lgkmcnt(0)
	v_mfma_f32_32x32x16_bf16 v[36:51], v[92:95], v[88:91], v[36:51]
	ds_read_b128 v[92:95], v173 offset:17088
	v_or_b32_e32 v98, s14, v97
	s_movk_i32 s13, 0xc0
	v_lshlrev_b32_e32 v96, 2, v170
	s_mov_b32 s14, 0x3e16c740
	s_lshl_b32 s5, s1, 15
	s_waitcnt lgkmcnt(0)
	v_mfma_f32_32x32x16_bf16 v[20:35], v[92:95], v[88:91], v[20:35]
	ds_read_b128 v[92:95], v173 offset:33984
	s_waitcnt lgkmcnt(0)
	v_mfma_f32_32x32x16_bf16 v[4:19], v[92:95], v[88:91], v[4:19]
	ds_read_b128 v[88:91], v173 offset:224
	s_waitcnt lgkmcnt(0)
	v_mfma_f32_32x32x16_bf16 v[36:51], v[88:91], v[84:87], v[36:51]
	ds_read_b128 v[88:91], v173 offset:17120
	s_waitcnt lgkmcnt(0)
	v_mfma_f32_32x32x16_bf16 v[20:35], v[88:91], v[84:87], v[20:35]
	ds_read_b128 v[88:91], v173 offset:34016
	s_waitcnt lgkmcnt(0)
	v_mfma_f32_32x32x16_bf16 v[4:19], v[88:91], v[84:87], v[4:19]
	ds_read_b128 v[84:87], v173 offset:256
	s_waitcnt lgkmcnt(0)
	v_mfma_f32_32x32x16_bf16 v[36:51], v[84:87], v[80:83], v[36:51]
	ds_read_b128 v[84:87], v173 offset:17152
	s_waitcnt lgkmcnt(0)
	v_mfma_f32_32x32x16_bf16 v[20:35], v[84:87], v[80:83], v[20:35]
	ds_read_b128 v[84:87], v173 offset:34048
	s_waitcnt lgkmcnt(0)
	v_mfma_f32_32x32x16_bf16 v[4:19], v[84:87], v[80:83], v[4:19]
	ds_read_b128 v[80:83], v173 offset:288
	s_waitcnt lgkmcnt(0)
	v_mfma_f32_32x32x16_bf16 v[36:51], v[80:83], v[76:79], v[36:51]
	ds_read_b128 v[80:83], v173 offset:17184
	s_waitcnt lgkmcnt(0)
	v_mfma_f32_32x32x16_bf16 v[20:35], v[80:83], v[76:79], v[20:35]
	ds_read_b128 v[80:83], v173 offset:34080
	s_waitcnt lgkmcnt(0)
	v_mfma_f32_32x32x16_bf16 v[4:19], v[80:83], v[76:79], v[4:19]
	ds_read_b128 v[76:79], v173 offset:320
	s_waitcnt lgkmcnt(0)
	v_mfma_f32_32x32x16_bf16 v[36:51], v[76:79], v[72:75], v[36:51]
	ds_read_b128 v[76:79], v173 offset:17216
	s_waitcnt lgkmcnt(0)
	v_mfma_f32_32x32x16_bf16 v[20:35], v[76:79], v[72:75], v[20:35]
	ds_read_b128 v[76:79], v173 offset:34112
	s_waitcnt lgkmcnt(0)
; #define MFMA32(a, b, c) __builtin_amdgcn_mfma_f32_32x32x16_bf16((a), (b), (c), 0, 0, 0)
; DI float xor32(float v) { return __shfl_xor(v, 32); }
; DI void prep_item(const Params& p, int layer, int item, char* smem) {
;     ...
;     for (int ks = 0; ks < 16; ++ks) {
; #pragma unroll
;       for (int nt = 0; nt < 3; ++nt) {
;         bf16x8 a = *(const bf16x8*)&sWq[nt * 32 + r][ks * 16 + 8 * h];
;         acc[nt] = MFMA32(a, bq[ks], acc[nt]);
;       }
;     }
;     float ss2 = 0.f;
; #pragma unroll
;     for (int nt = 0; nt < 3; ++nt)
; #pragma unroll
;       for (int i = 0; i < 16; ++i) { acc[nt][i] *= rq; ss2 += acc[nt][i] * acc[nt][i]; }
;     ss2 += xor32(ss2);
;     const float r2 = rsqrtf(ss2 * (1.f / 96.f) + EPS);
;     const float* gq = p.mla_q_g + layer * 96;
; #pragma unroll
;     for (int nt = 0; nt < 3; ++nt)
; #pragma unroll
;       for (int g = 0; g < 4; ++g) {
;         float4 gg = *(const float4*)(gq + nt * 32 + 8 * g + 4 * h);
;         acc[nt][4 * g] *= r2 * gg.x; acc[nt][4 * g + 1] *= r2 * gg.y; acc[nt][4 * g + 2] *= r2 * gg.z; acc[nt][4 * g + 3] *= r2 * gg.w;
	v_mfma_f32_32x32x16_bf16 v[4:19], v[76:79], v[72:75], v[4:19]
	ds_read_b128 v[72:75], v173 offset:352
	s_waitcnt lgkmcnt(0)
	v_mfma_f32_32x32x16_bf16 v[36:51], v[72:75], v[68:71], v[36:51]
	ds_read_b128 v[72:75], v173 offset:17248
	s_waitcnt lgkmcnt(0)
	v_mfma_f32_32x32x16_bf16 v[20:35], v[72:75], v[68:71], v[20:35]
	ds_read_b128 v[72:75], v173 offset:34144
	s_waitcnt lgkmcnt(0)
	v_mfma_f32_32x32x16_bf16 v[4:19], v[72:75], v[68:71], v[4:19]
	ds_read_b128 v[68:71], v173 offset:384
	v_cndmask_b32_e32 v72, v171, v172, vcc
	s_waitcnt lgkmcnt(0)
	v_mfma_f32_32x32x16_bf16 v[36:51], v[68:71], v[64:67], v[36:51]
	ds_read_b128 v[68:71], v173 offset:17280
	s_waitcnt lgkmcnt(0)
	v_mfma_f32_32x32x16_bf16 v[20:35], v[68:71], v[64:67], v[20:35]
	ds_read_b128 v[68:71], v173 offset:34176
	s_waitcnt lgkmcnt(0)
	v_mfma_f32_32x32x16_bf16 v[4:19], v[68:71], v[64:67], v[4:19]
	ds_read_b128 v[64:67], v173 offset:416
	s_waitcnt lgkmcnt(0)
	v_mfma_f32_32x32x16_bf16 v[36:51], v[64:67], v[60:63], v[36:51]
	ds_read_b128 v[64:67], v173 offset:17312
	s_waitcnt lgkmcnt(0)
	v_mfma_f32_32x32x16_bf16 v[20:35], v[64:67], v[60:63], v[20:35]
	ds_read_b128 v[64:67], v173 offset:34208
	s_waitcnt lgkmcnt(0)
	v_mfma_f32_32x32x16_bf16 v[4:19], v[64:67], v[60:63], v[4:19]
	ds_read_b128 v[60:63], v173 offset:448
	global_load_dwordx4 v[64:67], v154, s[36:37] offset:32
	s_waitcnt lgkmcnt(0)
	v_mfma_f32_32x32x16_bf16 v[36:51], v[60:63], v[56:59], v[36:51]
	ds_read_b128 v[60:63], v173 offset:17344
	s_waitcnt lgkmcnt(0)
	v_mfma_f32_32x32x16_bf16 v[20:35], v[60:63], v[56:59], v[20:35]
	ds_read_b128 v[60:63], v173 offset:34240
	s_waitcnt lgkmcnt(0)
	v_mfma_f32_32x32x16_bf16 v[4:19], v[60:63], v[56:59], v[4:19]
	ds_read_b128 v[56:59], v173 offset:480
	s_waitcnt lgkmcnt(0)
	v_mfma_f32_32x32x16_bf16 v[36:51], v[56:59], v[52:55], v[36:51]
	ds_read_b128 v[56:59], v173 offset:17376
	s_waitcnt lgkmcnt(0)
	v_mfma_f32_32x32x16_bf16 v[20:35], v[56:59], v[52:55], v[20:35]
	ds_read_b128 v[56:59], v173 offset:34272
	s_nop 7
	v_mul_f32_e64 v78, v42, v72
	v_mul_f32_e64 v79, v43, v72
	v_mul_f32_e64 v82, v40, v72
	v_mul_f32_e64 v83, v41, v72
	global_load_dwordx4 v[40:43], v154, s[36:37] offset:64
	v_pk_mul_f32 v[86:87], v[46:47], v[72:73] op_sel_hi:[1,0]
	v_pk_mul_f32 v[90:91], v[44:45], v[72:73] op_sel_hi:[1,0]
	global_load_dwordx4 v[44:47], v154, s[36:37] offset:96
	s_waitcnt lgkmcnt(0)
	v_mfma_f32_32x32x16_bf16 v[4:19], v[56:59], v[52:55], v[4:19]
	v_mul_f32_e64 v94, v50, v72
	v_mul_f32_e64 v95, v51, v72
	v_mul_f32_e64 v102, v48, v72
	v_mul_f32_e64 v103, v49, v72
	global_load_dwordx4 v[48:51], v154, s[36:37] offset:128
	v_pk_mul_f32 v[106:107], v[22:23], v[72:73] op_sel_hi:[1,0]
	v_pk_mul_f32 v[110:111], v[20:21], v[72:73] op_sel_hi:[1,0]
	global_load_dwordx4 v[20:23], v154, s[36:37] offset:160
	v_pk_mul_f32 v[132:133], v[26:27], v[72:73] op_sel_hi:[1,0]
	s_nop 2
	v_pk_mul_f32 v[52:53], v[14:15], v[72:73] op_sel_hi:[1,0]
	v_mov_b64_e32 v[14:15], s[20:21]
	v_mad_u64_u32 v[14:15], s[18:19], v98, s13, v[14:15]
	v_mad_i32_i24 v15, s15, v212, v15
	v_pk_mul_f32 v[54:55], v[16:17], v[72:73] op_sel_hi:[1,0]
	v_pk_mul_f32 v[56:57], v[18:19], v[72:73] op_sel_hi:[1,0]
	v_lshl_add_u64 v[18:19], v[14:15], 0, v[2:3]
	global_load_dwordx4 v[14:17], v154, s[36:37]
	v_pk_mul_f32 v[172:173], v[24:25], v[72:73] op_sel_hi:[1,0]
	global_load_dwordx4 v[24:27], v154, s[36:37] offset:192
	v_pk_mul_f32 v[176:177], v[30:31], v[72:73] op_sel_hi:[1,0]
	v_pk_mul_f32 v[180:181], v[28:29], v[72:73] op_sel_hi:[1,0]
	v_pk_mul_f32 v[184:185], v[34:35], v[72:73] op_sel_hi:[1,0]
	global_load_dwordx4 v[28:31], v154, s[36:37] offset:224
	v_pk_mul_f32 v[188:189], v[32:33], v[72:73] op_sel_hi:[1,0]
	v_pk_mul_f32 v[192:193], v[6:7], v[72:73] op_sel_hi:[1,0]
	global_load_dwordx4 v[32:35], v154, s[36:37] offset:256
	global_load_dwordx4 v[68:71], v154, s[36:37] offset:320
	v_pk_mul_f32 v[196:197], v[4:5], v[72:73] op_sel_hi:[1,0]
	v_pk_mul_f32 v[200:201], v[12:13], v[72:73] op_sel_hi:[1,0]
	v_pk_mul_f32 v[232:233], v[10:11], v[72:73] op_sel_hi:[1,0]
	global_load_dwordx4 v[4:7], v154, s[36:37] offset:288
	global_load_dwordx4 v[10:13], v154, s[36:37] offset:352
	v_pk_mul_f32 v[36:37], v[36:37], v[72:73] op_sel_hi:[1,0]
	v_pk_mul_f32 v[38:39], v[38:39], v[72:73] op_sel_hi:[1,0]
	v_pk_mul_f32 v[76:77], v[36:37], v[36:37]
	v_pk_mul_f32 v[74:75], v[38:39], v[38:39]
	v_add_f32_e32 v76, v76, v77
	v_add_f32_e32 v74, v74, v76
	v_pk_mul_f32 v[84:85], v[82:83], v[82:83]
	v_add_f32_e32 v74, v75, v74
	v_add_f32_e32 v74, v84, v74
	v_pk_mul_f32 v[80:81], v[78:79], v[78:79]
	v_add_f32_e32 v74, v85, v74
	v_add_f32_e32 v74, v80, v74
	v_pk_mul_f32 v[92:93], v[90:91], v[90:91]
	v_add_f32_e32 v74, v81, v74
	v_add_f32_e32 v74, v92, v74
	v_pk_mul_f32 v[88:89], v[86:87], v[86:87]
	v_add_f32_e32 v74, v93, v74
	v_add_f32_e32 v74, v88, v74
	v_pk_mul_f32 v[104:105], v[102:103], v[102:103]
	v_add_f32_e32 v74, v89, v74
	v_add_f32_e32 v74, v104, v74
	v_pk_mul_f32 v[100:101], v[94:95], v[94:95]
	v_add_f32_e32 v74, v105, v74
	v_add_f32_e32 v74, v100, v74
	v_pk_mul_f32 v[130:131], v[110:111], v[110:111]
	v_add_f32_e32 v74, v101, v74
	v_add_f32_e32 v74, v130, v74
	v_pk_mul_f32 v[108:109], v[106:107], v[106:107]
	v_add_f32_e32 v74, v131, v74
	v_add_f32_e32 v74, v108, v74
	v_pk_mul_f32 v[174:175], v[172:173], v[172:173]
	v_add_f32_e32 v74, v109, v74
	v_add_f32_e32 v74, v174, v74
	v_pk_mul_f32 v[170:171], v[132:133], v[132:133]
	v_add_f32_e32 v74, v175, v74
	v_add_f32_e32 v74, v170, v74
	v_pk_mul_f32 v[182:183], v[180:181], v[180:181]
	v_add_f32_e32 v74, v171, v74
	v_add_f32_e32 v74, v182, v74
	v_pk_mul_f32 v[178:179], v[176:177], v[176:177]
	v_add_f32_e32 v74, v183, v74
	v_add_f32_e32 v74, v178, v74
	v_pk_mul_f32 v[190:191], v[188:189], v[188:189]
	v_add_f32_e32 v74, v179, v74
	v_add_f32_e32 v74, v190, v74
	v_pk_mul_f32 v[186:187], v[184:185], v[184:185]
	v_add_f32_e32 v74, v191, v74
	v_add_f32_e32 v74, v186, v74
	v_pk_mul_f32 v[198:199], v[196:197], v[196:197]
	v_add_f32_e32 v74, v187, v74
	v_add_f32_e32 v74, v198, v74
	v_pk_mul_f32 v[194:195], v[192:193], v[192:193]
	v_add_f32_e32 v74, v199, v74
	v_pk_mul_f32 v[8:9], v[8:9], v[72:73] op_sel_hi:[1,0]
	v_add_f32_e32 v74, v194, v74
	v_pk_mul_f32 v[72:73], v[8:9], v[8:9]
	v_add_f32_e32 v74, v195, v74
	v_add_f32_e32 v72, v72, v74
	v_pk_mul_f32 v[234:235], v[232:233], v[232:233]
	v_add_f32_e32 v72, v73, v72
	v_add_f32_e32 v72, v234, v72
	v_pk_mul_f32 v[230:231], v[200:201], v[200:201]
	v_add_f32_e32 v72, v235, v72
	v_add_f32_e32 v72, v230, v72
	v_pk_mul_f32 v[58:59], v[52:53], v[52:53]
	v_add_f32_e32 v72, v231, v72
	v_add_f32_e32 v58, v58, v72
	v_pk_mul_f32 v[60:61], v[54:55], v[54:55]
	v_add_f32_e32 v58, v59, v58
	v_add_f32_e32 v58, v60, v58
	v_pk_mul_f32 v[62:63], v[56:57], v[56:57]
	v_add_f32_e32 v58, v61, v58
	v_add_f32_e32 v58, v62, v58
	v_add_f32_e32 v58, v63, v58
	ds_bpermute_b32 v59, v155, v58
	s_waitcnt lgkmcnt(0)
; DI uint32_t pack2(float a, float b) { f2_t v = {a, b}; bf2_t r = __builtin_convertvector(v, bf2_t); return __builtin_bit_cast(uint32_t, r); }
; DI float xor32(float v) { return __shfl_xor(v, 32); }
; DI void prep_item(const Params& p, int layer, int item, char* smem) {
;     ...
;     ss2 += xor32(ss2);
;     const float r2 = rsqrtf(ss2 * (1.f / 96.f) + EPS);
;     const float* gq = p.mla_q_g + layer * 96;
; #pragma unroll
;     for (int nt = 0; nt < 3; ++nt)
; #pragma unroll
;       for (int g = 0; g < 4; ++g) {
;         float4 gg = *(const float4*)(gq + nt * 32 + 8 * g + 4 * h);
;         acc[nt][4 * g] *= r2 * gg.x; acc[nt][4 * g + 1] *= r2 * gg.y; acc[nt][4 * g + 2] *= r2 * gg.z; acc[nt][4 * g + 3] *= r2 * gg.w;
;       }
; #pragma unroll
;     for (int reg = 0; reg < 8; ++reg) {
;       float x1 = acc[2][reg], x2 = acc[2][reg + 8];
;       acc[2][reg] = x1 * cs[reg] - x2 * sn[reg];
;       acc[2][reg + 8] = x2 * cs[reg] + x1 * sn[reg];
;     }
;     u16* qo = QB + ((size_t)(b * 8 + hd) * 4096 + s) * 96;
; #pragma unroll
;     for (int nt = 0; nt < 3; ++nt)
; #pragma unroll
;       for (int g = 0; g < 4; ++g)
;         *(uint2*)(qo + nt * 32 + 8 * g + 4 * h) = make_uint2(pack2(acc[nt][4 * g] * C_MLA, acc[nt][4 * g + 1] * C_MLA), pack2(acc[nt][4 * g + 2] * C_MLA, acc[nt][4 * g + 3] * C_MLA));
;   }
;   __syncthreads();
	v_add_f32_e32 v58, v58, v59
	v_fmamk_f32 v58, v58, 0x3c2aaaab, v206
	v_cmp_gt_f32_e32 vcc, s30, v58
	v_mul_f32_e32 v59, 0x4b800000, v58
	s_nop 0
	v_cndmask_b32_e32 v58, v58, v59, vcc
	v_rsq_f32_e32 v58, v58
	s_nop 0
	v_mul_f32_e32 v59, 0x45800000, v58
	v_cndmask_b32_e32 v58, v58, v59, vcc
	s_waitcnt vmcnt(6)
	v_pk_mul_f32 v[14:15], v[14:15], v[58:59] op_sel_hi:[1,0]
	v_pk_mul_f32 v[16:17], v[16:17], v[58:59] op_sel_hi:[1,0]
	v_pk_mul_f32 v[14:15], v[36:37], v[14:15]
	v_pk_mul_f32 v[16:17], v[38:39], v[16:17]
	v_pk_mul_f32 v[36:37], v[64:65], v[58:59] op_sel_hi:[1,0]
	v_pk_mul_f32 v[38:39], v[66:67], v[58:59] op_sel_hi:[1,0]
	v_pk_mul_f32 v[14:15], v[14:15], s[14:15] op_sel_hi:[1,0]
	v_pk_mul_f32 v[16:17], v[16:17], s[14:15] op_sel_hi:[1,0]
	v_pk_mul_f32 v[36:37], v[82:83], v[36:37]
	v_pk_mul_f32 v[38:39], v[78:79], v[38:39]
	v_cvt_pk_bf16_f32 v14, v14, v15
	v_cvt_pk_bf16_f32 v15, v16, v17
	v_pk_mul_f32 v[40:41], v[40:41], v[58:59] op_sel_hi:[1,0]
	v_pk_mul_f32 v[42:43], v[42:43], v[58:59] op_sel_hi:[1,0]
	global_store_dwordx2 v[18:19], v[14:15], off
	v_pk_mul_f32 v[14:15], v[36:37], s[14:15] op_sel_hi:[1,0]
	v_pk_mul_f32 v[16:17], v[38:39], s[14:15] op_sel_hi:[1,0]
	v_pk_mul_f32 v[40:41], v[90:91], v[40:41]
	v_pk_mul_f32 v[42:43], v[86:87], v[42:43]
	v_cvt_pk_bf16_f32 v14, v14, v15
	v_cvt_pk_bf16_f32 v15, v16, v17
	v_pk_mul_f32 v[44:45], v[44:45], v[58:59] op_sel_hi:[1,0]
	v_pk_mul_f32 v[46:47], v[46:47], v[58:59] op_sel_hi:[1,0]
	global_store_dwordx2 v[18:19], v[14:15], off offset:16
	v_pk_mul_f32 v[14:15], v[40:41], s[14:15] op_sel_hi:[1,0]
	v_pk_mul_f32 v[16:17], v[42:43], s[14:15] op_sel_hi:[1,0]
	v_pk_mul_f32 v[44:45], v[102:103], v[44:45]
	v_pk_mul_f32 v[46:47], v[94:95], v[46:47]
	v_cvt_pk_bf16_f32 v14, v14, v15
	v_cvt_pk_bf16_f32 v15, v16, v17
	v_pk_mul_f32 v[48:49], v[48:49], v[58:59] op_sel_hi:[1,0]
	v_pk_mul_f32 v[50:51], v[50:51], v[58:59] op_sel_hi:[1,0]
	global_store_dwordx2 v[18:19], v[14:15], off offset:32
	v_pk_mul_f32 v[14:15], v[44:45], s[14:15] op_sel_hi:[1,0]
	v_pk_mul_f32 v[16:17], v[46:47], s[14:15] op_sel_hi:[1,0]
	v_pk_mul_f32 v[48:49], v[110:111], v[48:49]
	v_pk_mul_f32 v[50:51], v[106:107], v[50:51]
	v_cvt_pk_bf16_f32 v14, v14, v15
	v_cvt_pk_bf16_f32 v15, v16, v17
	v_pk_mul_f32 v[20:21], v[20:21], v[58:59] op_sel_hi:[1,0]
	v_pk_mul_f32 v[22:23], v[22:23], v[58:59] op_sel_hi:[1,0]
	global_store_dwordx2 v[18:19], v[14:15], off offset:48
	v_pk_mul_f32 v[14:15], v[48:49], s[14:15] op_sel_hi:[1,0]
	v_pk_mul_f32 v[16:17], v[50:51], s[14:15] op_sel_hi:[1,0]
	v_pk_mul_f32 v[20:21], v[172:173], v[20:21]
	v_pk_mul_f32 v[22:23], v[132:133], v[22:23]
	v_cvt_pk_bf16_f32 v14, v14, v15
	v_cvt_pk_bf16_f32 v15, v16, v17
	s_waitcnt vmcnt(9)
	v_pk_mul_f32 v[24:25], v[24:25], v[58:59] op_sel_hi:[1,0]
	v_pk_mul_f32 v[26:27], v[26:27], v[58:59] op_sel_hi:[1,0]
	global_store_dwordx2 v[18:19], v[14:15], off offset:64
	v_pk_mul_f32 v[14:15], v[20:21], s[14:15] op_sel_hi:[1,0]
	v_pk_mul_f32 v[16:17], v[22:23], s[14:15] op_sel_hi:[1,0]
	v_pk_mul_f32 v[24:25], v[180:181], v[24:25]
	v_pk_mul_f32 v[26:27], v[176:177], v[26:27]
	s_waitcnt vmcnt(6)
	v_pk_mul_f32 v[4:5], v[4:5], v[58:59] op_sel_hi:[1,0]
	v_cvt_pk_bf16_f32 v14, v14, v15
	v_cvt_pk_bf16_f32 v15, v16, v17
	v_pk_mul_f32 v[28:29], v[28:29], v[58:59] op_sel_hi:[1,0]
	v_pk_mul_f32 v[30:31], v[30:31], v[58:59] op_sel_hi:[1,0]
	v_pk_mul_f32 v[4:5], v[8:9], v[4:5]
	v_pk_mul_f32 v[8:9], v[68:69], v[58:59] op_sel_hi:[1,0]
	v_pk_mul_f32 v[60:61], v[70:71], v[58:59] op_sel_hi:[1,0]
	global_store_dwordx2 v[18:19], v[14:15], off offset:80
	v_pk_mul_f32 v[14:15], v[24:25], s[14:15] op_sel_hi:[1,0]
	v_pk_mul_f32 v[16:17], v[26:27], s[14:15] op_sel_hi:[1,0]
	v_pk_mul_f32 v[28:29], v[188:189], v[28:29]
	v_pk_mul_f32 v[30:31], v[184:185], v[30:31]
	v_pk_mul_f32 v[32:33], v[32:33], v[58:59] op_sel_hi:[1,0]
	v_pk_mul_f32 v[34:35], v[34:35], v[58:59] op_sel_hi:[1,0]
	v_pk_mul_f32 v[8:9], v[200:201], v[8:9]
	v_pk_mul_f32 v[52:53], v[52:53], v[60:61]
	s_waitcnt vmcnt(6)
	v_pk_mul_f32 v[10:11], v[10:11], v[58:59] op_sel_hi:[1,0]
	v_pk_mul_f32 v[12:13], v[12:13], v[58:59] op_sel_hi:[1,0]
	v_cvt_pk_bf16_f32 v14, v14, v15
	v_cvt_pk_bf16_f32 v15, v16, v17
	v_pk_mul_f32 v[32:33], v[196:197], v[32:33]
	v_pk_mul_f32 v[34:35], v[192:193], v[34:35]
	v_pk_mul_f32 v[10:11], v[54:55], v[10:11]
	v_pk_mul_f32 v[12:13], v[56:57], v[12:13]
	v_pk_mul_f32 v[54:55], v[116:117], v[8:9]
	v_pk_mul_f32 v[56:57], v[120:121], v[52:53]
	global_store_dwordx2 v[18:19], v[14:15], off offset:96
	v_pk_mul_f32 v[14:15], v[28:29], s[14:15] op_sel_hi:[1,0]
	v_pk_mul_f32 v[16:17], v[30:31], s[14:15] op_sel_hi:[1,0]
	v_pk_mul_f32 v[6:7], v[6:7], v[58:59] op_sel_hi:[1,0]
	v_pk_fma_f32 v[54:55], v[118:119], v[32:33], v[54:55] neg_lo:[0,0,1] neg_hi:[0,0,1]
	v_pk_fma_f32 v[56:57], v[122:123], v[34:35], v[56:57] neg_lo:[0,0,1] neg_hi:[0,0,1]
	v_cvt_pk_bf16_f32 v14, v14, v15
	v_cvt_pk_bf16_f32 v15, v16, v17
	v_pk_mul_f32 v[6:7], v[232:233], v[6:7]
	v_pk_mul_f32 v[58:59], v[124:125], v[10:11]
	v_pk_mul_f32 v[60:61], v[150:151], v[12:13]
	global_store_dwordx2 v[18:19], v[14:15], off offset:112
	v_pk_mul_f32 v[14:15], v[54:55], s[14:15] op_sel_hi:[1,0]
	v_pk_mul_f32 v[16:17], v[56:57], s[14:15] op_sel_hi:[1,0]
	v_pk_fma_f32 v[58:59], v[126:127], v[4:5], v[58:59] neg_lo:[0,0,1] neg_hi:[0,0,1]
	v_pk_fma_f32 v[60:61], v[152:153], v[6:7], v[60:61] neg_lo:[0,0,1] neg_hi:[0,0,1]
	v_cvt_pk_bf16_f32 v14, v14, v15
	v_cvt_pk_bf16_f32 v15, v16, v17
	global_store_dwordx2 v[18:19], v[14:15], off offset:128
	v_pk_mul_f32 v[14:15], v[58:59], s[14:15] op_sel_hi:[1,0]
	v_pk_mul_f32 v[16:17], v[60:61], s[14:15] op_sel_hi:[1,0]
	v_cvt_pk_bf16_f32 v14, v14, v15
	v_cvt_pk_bf16_f32 v15, v16, v17
	global_store_dwordx2 v[18:19], v[14:15], off offset:144
	v_pk_mul_f32 v[14:15], v[116:117], v[32:33]
	v_pk_mul_f32 v[4:5], v[124:125], v[4:5]
	v_pk_mul_f32 v[6:7], v[150:151], v[6:7]
	v_pk_fma_f32 v[8:9], v[118:119], v[8:9], v[14:15]
	v_pk_mul_f32 v[14:15], v[120:121], v[34:35]
	v_pk_fma_f32 v[4:5], v[126:127], v[10:11], v[4:5]
	v_pk_fma_f32 v[6:7], v[152:153], v[12:13], v[6:7]
	v_pk_fma_f32 v[14:15], v[122:123], v[52:53], v[14:15]
	v_pk_mul_f32 v[4:5], v[4:5], s[14:15] op_sel_hi:[1,0]
	v_pk_mul_f32 v[6:7], v[6:7], s[14:15] op_sel_hi:[1,0]
	v_pk_mul_f32 v[8:9], v[8:9], s[14:15] op_sel_hi:[1,0]
	v_pk_mul_f32 v[14:15], v[14:15], s[14:15] op_sel_hi:[1,0]
	v_cvt_pk_bf16_f32 v4, v4, v5
	v_cvt_pk_bf16_f32 v5, v6, v7
	v_readlane_b32 s14, v255, 3
	v_cvt_pk_bf16_f32 v8, v8, v9
	v_cvt_pk_bf16_f32 v9, v14, v15
	global_store_dwordx2 v[18:19], v[4:5], off offset:176
	s_add_u32 s18, s14, s5
	v_readlane_b32 s5, v255, 4
	v_ashrrev_i32_e32 v4, 4, v159
	global_store_dwordx2 v[18:19], v[8:9], off offset:160
	s_addc_u32 s19, s5, 0
	v_and_b32_e32 v8, 0xf0, v162
	v_mov_b32_e32 v9, v3
	v_ashrrev_i32_e32 v5, 31, v4
	v_lshl_add_u64 v[10:11], s[18:19], 0, v[8:9]
	v_lshlrev_b64 v[6:7], 8, v[4:5]
	v_lshl_add_u64 v[6:7], v[10:11], 0, v[6:7]
	s_movk_i32 s5, 0x110
	s_barrier
; DI float bflo(uint32_t u) { return __uint_as_float(u << 16); }
; DI float bfhi(uint32_t u) { return __uint_as_float(u & 0xffff0000u); }
; DI void prep_item(const Params& p, int layer, int item, char* smem) {
;     ...
;   {
;     const u16* src = WUKV + (size_t)(hd * 128) * 128;
; #pragma unroll
;     for (int i = 0; i < 8; ++i) {
;       const int idx = tid + 256 * i, row = idx >> 4, c = idx & 15;
;       *(uint4*)&sWk[row][c * 8] = *(const uint4*)(src + (size_t)row * 128 + c * 8);
;     }
;   }
;   __syncthreads();
;   {
;     bf16x8 bk[8];
;     float ss = 0.f;
; #pragma unroll
;     for (int ks = 0; ks < 8; ++ks) {
;       uint4 u = *(const uint4*)(prow + O_CKV + ks * 16 + 8 * h);
;       bk[ks] = __builtin_bit_cast(bf16x8, u);
;       float f;
;       f = bflo(u.x); ss += f * f; f = bfhi(u.x); ss += f * f; f = bflo(u.y); ss += f * f; f = bfhi(u.y); ss += f * f;
;       f = bflo(u.z); ss += f * f; f = bfhi(u.z); ss += f * f; f = bflo(u.w); ss += f * f; f = bfhi(u.w); ss += f * f;
;     }
	v_mad_u64_u32 v[12:13], s[18:19], v4, s5, v[8:9]
	global_load_dwordx4 v[40:43], v[6:7], off
	v_mad_u32_u24 v101, v161, s5, v154
	s_lshl_b32 s16, s1, 7
	s_cmp_lt_i32 s1, 1
	v_ashrrev_i32_e32 v4, 4, v163
	v_ashrrev_i32_e32 v5, 31, v4
	v_lshlrev_b64 v[6:7], 8, v[4:5]
	v_lshl_add_u64 v[6:7], v[10:11], 0, v[6:7]
	global_load_dwordx4 v[44:47], v[6:7], off
	v_ashrrev_i32_e32 v4, 4, v164
	v_ashrrev_i32_e32 v5, 31, v4
	v_lshlrev_b64 v[6:7], 8, v[4:5]
	v_lshl_add_u64 v[6:7], v[10:11], 0, v[6:7]
	global_load_dwordx4 v[48:51], v[6:7], off
	v_ashrrev_i32_e32 v4, 4, v165
	v_ashrrev_i32_e32 v5, 31, v4
	v_lshlrev_b64 v[6:7], 8, v[4:5]
	v_lshl_add_u64 v[6:7], v[10:11], 0, v[6:7]
	global_load_dwordx4 v[52:55], v[6:7], off
	v_ashrrev_i32_e32 v4, 4, v166
	v_ashrrev_i32_e32 v5, 31, v4
	v_lshlrev_b64 v[6:7], 8, v[4:5]
	v_lshl_add_u64 v[6:7], v[10:11], 0, v[6:7]
	global_load_dwordx4 v[56:59], v[6:7], off
	v_ashrrev_i32_e32 v4, 4, v167
	v_ashrrev_i32_e32 v5, 31, v4
	v_lshlrev_b64 v[6:7], 8, v[4:5]
	v_lshl_add_u64 v[6:7], v[10:11], 0, v[6:7]
	global_load_dwordx4 v[60:63], v[6:7], off
	v_ashrrev_i32_e32 v4, 4, v168
	v_ashrrev_i32_e32 v5, 31, v4
	v_lshlrev_b64 v[6:7], 8, v[4:5]
	v_lshl_add_u64 v[6:7], v[10:11], 0, v[6:7]
	global_load_dwordx4 v[64:67], v[6:7], off
	v_ashrrev_i32_e32 v4, 4, v169
	v_ashrrev_i32_e32 v5, 31, v4
	v_lshlrev_b64 v[6:7], 8, v[4:5]
	v_lshl_add_u64 v[6:7], v[10:11], 0, v[6:7]
	global_load_dwordx4 v[68:71], v[6:7], off
	v_readlane_b32 s18, v252, 10
	v_readlane_b32 s19, v252, 11
	s_mov_b32 s5, 0x80000
	s_waitcnt vmcnt(7)
	ds_write_b128 v12, v[40:43]
	s_waitcnt vmcnt(6)
	ds_write_b128 v12, v[44:47] offset:4352
	s_waitcnt vmcnt(5)
	ds_write_b128 v12, v[48:51] offset:8704
	s_waitcnt vmcnt(4)
	ds_write_b128 v12, v[52:55] offset:13056
	s_waitcnt vmcnt(3)
	ds_write_b128 v12, v[56:59] offset:17408
	s_waitcnt vmcnt(2)
	ds_write_b128 v12, v[60:63] offset:21760
	s_waitcnt vmcnt(1)
	ds_write_b128 v12, v[64:67] offset:26112
	s_waitcnt vmcnt(0)
	ds_write_b128 v12, v[68:71] offset:30464
	s_waitcnt lgkmcnt(0)
	s_barrier
	global_load_dwordx4 v[36:39], v[156:157], off offset:512
	global_load_dwordx4 v[92:95], v[156:157], off offset:544
	global_load_dwordx4 v[88:91], v[156:157], off offset:576
	global_load_dwordx4 v[84:87], v[156:157], off offset:608
	global_load_dwordx4 v[80:83], v[156:157], off offset:640
	global_load_dwordx4 v[68:71], v[156:157], off offset:672
	global_load_dwordx4 v[72:75], v[156:157], off offset:704
	global_load_dwordx4 v[76:79], v[156:157], off offset:736
	s_waitcnt vmcnt(7)
	v_lshlrev_b32_e32 v4, 16, v36
	v_mul_f32_e32 v6, v4, v4
	v_and_b32_e32 v4, 0xffff0000, v36
	v_fmac_f32_e32 v6, v4, v4
	v_lshlrev_b32_e32 v4, 16, v37
	v_fmac_f32_e32 v6, v4, v4
	v_and_b32_e32 v4, 0xffff0000, v37
	v_fmac_f32_e32 v6, v4, v4
	v_lshlrev_b32_e32 v4, 16, v38
	v_fmac_f32_e32 v6, v4, v4
	v_and_b32_e32 v4, 0xffff0000, v38
	v_fmac_f32_e32 v6, v4, v4
	v_lshlrev_b32_e32 v4, 16, v39
	v_fmac_f32_e32 v6, v4, v4
	v_and_b32_e32 v4, 0xffff0000, v39
	v_fmac_f32_e32 v6, v4, v4
	s_waitcnt vmcnt(6)
	v_lshlrev_b32_e32 v4, 16, v92
	v_fmac_f32_e32 v6, v4, v4
	v_and_b32_e32 v4, 0xffff0000, v92
	v_fmac_f32_e32 v6, v4, v4
	v_lshlrev_b32_e32 v4, 16, v93
	v_fmac_f32_e32 v6, v4, v4
	v_and_b32_e32 v4, 0xffff0000, v93
	v_fmac_f32_e32 v6, v4, v4
	v_lshlrev_b32_e32 v4, 16, v94
	v_fmac_f32_e32 v6, v4, v4
	v_and_b32_e32 v4, 0xffff0000, v94
	v_fmac_f32_e32 v6, v4, v4
	v_lshlrev_b32_e32 v4, 16, v95
	v_fmac_f32_e32 v6, v4, v4
	v_and_b32_e32 v4, 0xffff0000, v95
	v_fmac_f32_e32 v6, v4, v4
	s_waitcnt vmcnt(5)
	v_lshlrev_b32_e32 v4, 16, v88
	v_fmac_f32_e32 v6, v4, v4
	v_and_b32_e32 v4, 0xffff0000, v88
	v_fmac_f32_e32 v6, v4, v4
	v_lshlrev_b32_e32 v4, 16, v89
	v_fmac_f32_e32 v6, v4, v4
	v_and_b32_e32 v4, 0xffff0000, v89
	v_fmac_f32_e32 v6, v4, v4
	v_lshlrev_b32_e32 v4, 16, v90
	v_fmac_f32_e32 v6, v4, v4
	v_and_b32_e32 v4, 0xffff0000, v90
	v_fmac_f32_e32 v6, v4, v4
	v_lshlrev_b32_e32 v4, 16, v91
	v_fmac_f32_e32 v6, v4, v4
	v_and_b32_e32 v4, 0xffff0000, v91
	v_fmac_f32_e32 v6, v4, v4
	s_waitcnt vmcnt(4)
	v_lshlrev_b32_e32 v4, 16, v84
	v_fmac_f32_e32 v6, v4, v4
	v_and_b32_e32 v4, 0xffff0000, v84
	v_fmac_f32_e32 v6, v4, v4
	v_lshlrev_b32_e32 v4, 16, v85
	v_fmac_f32_e32 v6, v4, v4
	v_and_b32_e32 v4, 0xffff0000, v85
	v_fmac_f32_e32 v6, v4, v4
	v_lshlrev_b32_e32 v4, 16, v86
	v_fmac_f32_e32 v6, v4, v4
	v_and_b32_e32 v4, 0xffff0000, v86
	v_fmac_f32_e32 v6, v4, v4
	v_lshlrev_b32_e32 v4, 16, v87
	v_fmac_f32_e32 v6, v4, v4
	v_and_b32_e32 v4, 0xffff0000, v87
	v_fmac_f32_e32 v6, v4, v4
	s_waitcnt vmcnt(3)
	v_lshlrev_b32_e32 v4, 16, v80
	v_fmac_f32_e32 v6, v4, v4
	v_and_b32_e32 v4, 0xffff0000, v80
	v_fmac_f32_e32 v6, v4, v4
	v_lshlrev_b32_e32 v4, 16, v81
	v_fmac_f32_e32 v6, v4, v4
	v_and_b32_e32 v4, 0xffff0000, v81
	v_fmac_f32_e32 v6, v4, v4
	v_lshlrev_b32_e32 v4, 16, v82
	v_fmac_f32_e32 v6, v4, v4
	v_and_b32_e32 v4, 0xffff0000, v82
	v_fmac_f32_e32 v6, v4, v4
	v_lshlrev_b32_e32 v4, 16, v83
	v_fmac_f32_e32 v6, v4, v4
	v_and_b32_e32 v4, 0xffff0000, v83
	v_fmac_f32_e32 v6, v4, v4
	s_waitcnt vmcnt(2)
	v_lshlrev_b32_e32 v4, 16, v68
	v_fmac_f32_e32 v6, v4, v4
	v_and_b32_e32 v4, 0xffff0000, v68
	v_fmac_f32_e32 v6, v4, v4
	v_lshlrev_b32_e32 v4, 16, v69
	v_fmac_f32_e32 v6, v4, v4
	v_and_b32_e32 v4, 0xffff0000, v69
	v_fmac_f32_e32 v6, v4, v4
	v_lshlrev_b32_e32 v4, 16, v70
	v_fmac_f32_e32 v6, v4, v4
	v_and_b32_e32 v4, 0xffff0000, v70
	v_fmac_f32_e32 v6, v4, v4
	v_lshlrev_b32_e32 v4, 16, v71
	v_fmac_f32_e32 v6, v4, v4
	v_and_b32_e32 v4, 0xffff0000, v71
	v_fmac_f32_e32 v6, v4, v4
	s_waitcnt vmcnt(1)
; #define MFMA32(a, b, c) __builtin_amdgcn_mfma_f32_32x32x16_bf16((a), (b), (c), 0, 0, 0)
; DI float xor32(float v) { return __shfl_xor(v, 32); }
; DI f32x16 zero16() { f32x16 z; _Pragma("unroll") for (int i = 0; i < 16; ++i) z[i] = 0.f; return z; }
; DI void prep_item(const Params& p, int layer, int item, char* smem) {
;     ...
;     ss += xor32(ss);
;     const float rkv = rsqrtf(ss * (1.f / 128.f) + EPS);
;     f32x16 acc[4];
;     acc[0] = zero16(); acc[1] = zero16(); acc[2] = zero16(); acc[3] = zero16();
; #pragma unroll
;     for (int ks = 0; ks < 8; ++ks) {
; #pragma unroll
;       for (int nt = 0; nt < 4; ++nt) {
;         bf16x8 a = *(const bf16x8*)&sWk[nt * 32 + r][ks * 16 + 8 * h];
;         acc[nt] = MFMA32(a, bk[ks], acc[nt]);
;       }
;     }
	v_lshlrev_b32_e32 v4, 16, v72
	v_fmac_f32_e32 v6, v4, v4
	v_and_b32_e32 v4, 0xffff0000, v72
	v_fmac_f32_e32 v6, v4, v4
	v_lshlrev_b32_e32 v4, 16, v73
	v_fmac_f32_e32 v6, v4, v4
	v_and_b32_e32 v4, 0xffff0000, v73
	v_fmac_f32_e32 v6, v4, v4
	v_lshlrev_b32_e32 v4, 16, v74
	v_fmac_f32_e32 v6, v4, v4
	v_and_b32_e32 v4, 0xffff0000, v74
	v_fmac_f32_e32 v6, v4, v4
	v_and_b32_e32 v4, 0xffff0000, v75
	v_lshlrev_b32_e32 v5, 16, v75
	v_pk_mul_f32 v[4:5], v[4:5], v[4:5]
	s_nop 0
	v_add_f32_e32 v5, v5, v6
	v_add_f32_e32 v6, v4, v5
	s_waitcnt vmcnt(0)
	v_and_b32_e32 v4, 0xffff0000, v76
	v_lshlrev_b32_e32 v5, 16, v76
	v_pk_mul_f32 v[4:5], v[4:5], v[4:5]
	s_nop 0
	v_add_f32_e32 v5, v5, v6
	v_add_f32_e32 v6, v4, v5
	v_and_b32_e32 v4, 0xffff0000, v77
	v_lshlrev_b32_e32 v5, 16, v77
	v_pk_mul_f32 v[4:5], v[4:5], v[4:5]
	s_nop 0
	v_add_f32_e32 v5, v5, v6
	v_add_f32_e32 v6, v4, v5
	v_and_b32_e32 v4, 0xffff0000, v78
	v_lshlrev_b32_e32 v5, 16, v78
	v_pk_mul_f32 v[4:5], v[4:5], v[4:5]
	s_nop 0
	v_add_f32_e32 v5, v5, v6
	v_add_f32_e32 v6, v4, v5
	v_and_b32_e32 v4, 0xffff0000, v79
	v_lshlrev_b32_e32 v5, 16, v79
	v_pk_mul_f32 v[4:5], v[4:5], v[4:5]
	s_nop 0
	v_add_f32_e32 v5, v5, v6
	v_add_f32_e32 v4, v4, v5
	ds_bpermute_b32 v5, v155, v4
	s_waitcnt lgkmcnt(0)
	v_add_f32_e32 v4, v4, v5
	v_fmamk_f32 v4, v4, 0x3c000000, v206
	v_cmp_gt_f32_e32 vcc, s30, v4
	v_mul_f32_e32 v5, 0x4b800000, v4
	s_nop 0
	v_cndmask_b32_e32 v4, v4, v5, vcc
	v_rsq_f32_e32 v99, v4
	ds_read_b128 v[4:7], v101
	ds_read_b128 v[102:105], v101 offset:32
	s_waitcnt lgkmcnt(1)
	v_mfma_f32_32x32x16_bf16 v[20:35], v[4:7], v[36:39], 0
	ds_read_b128 v[4:7], v101 offset:8704
	ds_read_b128 v[40:43], v101 offset:17408
	v_mul_f32_e32 v100, 0x45800000, v99
	global_load_dwordx4 v[162:165], v154, s[10:11] offset:256
	global_load_dwordx4 v[166:169], v154, s[10:11] offset:320
	global_load_dwordx4 v[170:173], v154, s[10:11] offset:32
	global_load_dwordx4 v[174:177], v154, s[10:11] offset:160
	s_waitcnt lgkmcnt(2)
	v_mfma_f32_32x32x16_bf16 v[20:35], v[102:105], v[92:95], v[20:35]
	ds_read_b128 v[102:105], v101 offset:8736
	s_waitcnt lgkmcnt(2)
	v_mfma_f32_32x32x16_bf16 v[4:19], v[4:7], v[36:39], 0
	s_waitcnt lgkmcnt(0)
	v_mfma_f32_32x32x16_bf16 v[4:19], v[102:105], v[92:95], v[4:19]
	ds_read_b128 v[102:105], v101 offset:17440
	v_mfma_f32_32x32x16_bf16 v[52:67], v[40:43], v[36:39], 0
	ds_read_b128 v[40:43], v101 offset:26112
	s_waitcnt lgkmcnt(1)
	v_mfma_f32_32x32x16_bf16 v[52:67], v[102:105], v[92:95], v[52:67]
	ds_read_b128 v[102:105], v101 offset:26144
	s_waitcnt lgkmcnt(1)
	v_mfma_f32_32x32x16_bf16 v[36:51], v[40:43], v[36:39], 0
	s_waitcnt lgkmcnt(0)
	v_mfma_f32_32x32x16_bf16 v[36:51], v[102:105], v[92:95], v[36:51]
	ds_read_b128 v[92:95], v101 offset:64
	s_waitcnt lgkmcnt(0)
	v_mfma_f32_32x32x16_bf16 v[20:35], v[92:95], v[88:91], v[20:35]
	ds_read_b128 v[92:95], v101 offset:8768
	s_waitcnt lgkmcnt(0)
	v_mfma_f32_32x32x16_bf16 v[4:19], v[92:95], v[88:91], v[4:19]
	ds_read_b128 v[92:95], v101 offset:17472
	s_waitcnt lgkmcnt(0)
	v_mfma_f32_32x32x16_bf16 v[52:67], v[92:95], v[88:91], v[52:67]
	ds_read_b128 v[92:95], v101 offset:26176
	s_waitcnt lgkmcnt(0)
	v_mfma_f32_32x32x16_bf16 v[36:51], v[92:95], v[88:91], v[36:51]
	ds_read_b128 v[88:91], v101 offset:96
	s_waitcnt lgkmcnt(0)
	v_mfma_f32_32x32x16_bf16 v[20:35], v[88:91], v[84:87], v[20:35]
	ds_read_b128 v[88:91], v101 offset:8800
	s_waitcnt lgkmcnt(0)
	v_mfma_f32_32x32x16_bf16 v[4:19], v[88:91], v[84:87], v[4:19]
	ds_read_b128 v[88:91], v101 offset:17504
	s_waitcnt lgkmcnt(0)
	v_mfma_f32_32x32x16_bf16 v[52:67], v[88:91], v[84:87], v[52:67]
	ds_read_b128 v[88:91], v101 offset:26208
	s_waitcnt lgkmcnt(0)
	v_mfma_f32_32x32x16_bf16 v[36:51], v[88:91], v[84:87], v[36:51]
	ds_read_b128 v[84:87], v101 offset:128
	s_waitcnt lgkmcnt(0)
	v_mfma_f32_32x32x16_bf16 v[20:35], v[84:87], v[80:83], v[20:35]
	ds_read_b128 v[84:87], v101 offset:8832
	s_waitcnt lgkmcnt(0)
	v_mfma_f32_32x32x16_bf16 v[4:19], v[84:87], v[80:83], v[4:19]
	ds_read_b128 v[84:87], v101 offset:17536
	s_waitcnt lgkmcnt(0)
	v_mfma_f32_32x32x16_bf16 v[52:67], v[84:87], v[80:83], v[52:67]
	ds_read_b128 v[84:87], v101 offset:26240
	s_waitcnt lgkmcnt(0)
	v_mfma_f32_32x32x16_bf16 v[36:51], v[84:87], v[80:83], v[36:51]
	ds_read_b128 v[80:83], v101 offset:160
	v_cndmask_b32_e32 v84, v99, v100, vcc
	s_waitcnt lgkmcnt(0)
	v_mfma_f32_32x32x16_bf16 v[20:35], v[80:83], v[68:71], v[20:35]
	ds_read_b128 v[80:83], v101 offset:8864
	s_waitcnt lgkmcnt(0)
	v_mfma_f32_32x32x16_bf16 v[4:19], v[80:83], v[68:71], v[4:19]
	ds_read_b128 v[80:83], v101 offset:17568
	s_waitcnt lgkmcnt(0)
	v_mfma_f32_32x32x16_bf16 v[52:67], v[80:83], v[68:71], v[52:67]
	ds_read_b128 v[80:83], v101 offset:26272
	s_waitcnt lgkmcnt(0)
	v_mfma_f32_32x32x16_bf16 v[36:51], v[80:83], v[68:71], v[36:51]
	ds_read_b128 v[68:71], v101 offset:192
	s_waitcnt lgkmcnt(0)
	v_mfma_f32_32x32x16_bf16 v[20:35], v[68:71], v[72:75], v[20:35]
	ds_read_b128 v[68:71], v101 offset:8896
	s_waitcnt lgkmcnt(0)
	v_mfma_f32_32x32x16_bf16 v[4:19], v[68:71], v[72:75], v[4:19]
	ds_read_b128 v[68:71], v101 offset:17600
	s_waitcnt lgkmcnt(0)
	v_mfma_f32_32x32x16_bf16 v[52:67], v[68:71], v[72:75], v[52:67]
	ds_read_b128 v[68:71], v101 offset:26304
	s_waitcnt lgkmcnt(0)
	v_mfma_f32_32x32x16_bf16 v[36:51], v[68:71], v[72:75], v[36:51]
	ds_read_b128 v[68:71], v101 offset:224
	s_waitcnt lgkmcnt(0)
	v_mfma_f32_32x32x16_bf16 v[20:35], v[68:71], v[76:79], v[20:35]
	ds_read_b128 v[68:71], v101 offset:8928
	s_waitcnt lgkmcnt(0)
	v_mfma_f32_32x32x16_bf16 v[4:19], v[68:71], v[76:79], v[4:19]
	ds_read_b128 v[68:71], v101 offset:17632
	s_waitcnt lgkmcnt(0)
; DI float bflo(uint32_t u) { return __uint_as_float(u << 16); }
; DI float bfhi(uint32_t u) { return __uint_as_float(u & 0xffff0000u); }
; DI float xor32(float v) { return __shfl_xor(v, 32); }
; DI void prep_item(const Params& p, int layer, int item, char* smem) {
;     ...
;     float kpe[16];
; #pragma unroll
;     for (int g = 0; g < 4; ++g) {
;       uint2 u = *(const uint2*)(prow + O_KPE + 8 * g + 4 * h);
;       kpe[4 * g] = bflo(u.x); kpe[4 * g + 1] = bfhi(u.x); kpe[4 * g + 2] = bflo(u.y); kpe[4 * g + 3] = bfhi(u.y);
;     }
;     float ss2 = 0.f;
; #pragma unroll
;     for (int nt = 0; nt < 4; ++nt)
; #pragma unroll
;       for (int i = 0; i < 16; ++i) acc[nt][i] *= rkv;
; #pragma unroll
;     for (int i = 0; i < 16; ++i) ss2 += acc[0][i] * acc[0][i] + acc[1][i] * acc[1][i] + kpe[i] * kpe[i];
;     ss2 += xor32(ss2);
;     const float r2 = rsqrtf(ss2 * (1.f / 96.f) + EPS);
;     const float* gk = p.mla_k_g + layer * 96;
; #pragma unroll
;     for (int g = 0; g < 4; ++g) {
;       float4 g0 = *(const float4*)(gk + 8 * g + 4 * h);
;       float4 g1 = *(const float4*)(gk + 32 + 8 * g + 4 * h);
;       float4 g2 = *(const float4*)(gk + 64 + 8 * g + 4 * h);
;       acc[0][4 * g] *= r2 * g0.x; acc[0][4 * g + 1] *= r2 * g0.y; acc[0][4 * g + 2] *= r2 * g0.z; acc[0][4 * g + 3] *= r2 * g0.w;
;       acc[1][4 * g] *= r2 * g1.x; acc[1][4 * g + 1] *= r2 * g1.y; acc[1][4 * g + 2] *= r2 * g1.z; acc[1][4 * g + 3] *= r2 * g1.w;
;       kpe[4 * g] *= r2 * g2.x; kpe[4 * g + 1] *= r2 * g2.y; kpe[4 * g + 2] *= r2 * g2.z; kpe[4 * g + 3] *= r2 * g2.w;
;     }
	v_mfma_f32_32x32x16_bf16 v[52:67], v[68:71], v[76:79], v[52:67]
	ds_read_b128 v[68:71], v101 offset:26336
	s_waitcnt lgkmcnt(0)
	v_mfma_f32_32x32x16_bf16 v[36:51], v[68:71], v[76:79], v[36:51]
	v_lshl_add_u64 v[68:69], v[114:115], 0, v[2:3]
	global_load_dwordx2 v[70:71], v[68:69], off offset:2560
	global_load_dwordx2 v[190:191], v[68:69], off offset:2576
	global_load_dwordx2 v[192:193], v[68:69], off offset:2592
	global_load_dwordx2 v[194:195], v[68:69], off offset:2608
	s_nop 6
	v_mul_f32_e32 v106, v54, v84
	v_mul_f32_e32 v105, v55, v84
	v_mul_f32_e32 v104, v56, v84
	v_mul_f32_e32 v103, v57, v84
	v_mul_f32_e32 v99, v61, v84
	v_mul_f32_e32 v85, v40, v84
	v_pk_mul_f32 v[54:55], v[14:15], v[84:85] op_sel_hi:[1,0]
	v_pk_mul_f32 v[56:57], v[30:31], v[84:85] op_sel_hi:[1,0]
	v_pk_mul_f32 v[14:15], v[54:55], v[54:55]
	v_pk_mul_f32 v[30:31], v[16:17], v[84:85] op_sel_hi:[1,0]
	v_pk_fma_f32 v[14:15], v[56:57], v[56:57], v[14:15]
	v_mul_f32_e32 v95, v62, v84
	v_mul_f32_e32 v89, v36, v84
	v_mul_f32_e32 v88, v37, v84
	v_mul_f32_e32 v62, v46, v84
	v_mul_f32_e32 v61, v47, v84
	v_pk_mul_f32 v[46:47], v[32:33], v[84:85] op_sel_hi:[1,0]
	v_pk_mul_f32 v[18:19], v[18:19], v[84:85] op_sel_hi:[1,0]
	v_mul_f32_e32 v102, v58, v84
	v_mul_f32_e32 v90, v67, v84
	v_mul_f32_e32 v67, v41, v84
	v_mul_f32_e32 v58, v50, v84
	v_mul_f32_e32 v41, v51, v84
	v_pk_mul_f32 v[50:51], v[34:35], v[84:85] op_sel_hi:[1,0]
	v_mul_f32_e32 v94, v63, v84
	v_mul_f32_e32 v93, v64, v84
	v_mul_f32_e32 v92, v65, v84
	v_mul_f32_e32 v91, v66, v84
	v_mul_f32_e32 v66, v42, v84
	v_mul_f32_e32 v65, v43, v84
	v_mul_f32_e32 v64, v44, v84
	v_mul_f32_e32 v63, v45, v84
	global_load_dwordx4 v[42:45], v154, s[10:11] offset:128
	v_mul_f32_e32 v101, v59, v84
	v_mul_f32_e32 v100, v60, v84
	v_mul_f32_e32 v60, v48, v84
	v_mul_f32_e32 v59, v49, v84
	v_pk_mul_f32 v[48:49], v[4:5], v[84:85] op_sel_hi:[1,0]
	v_mul_f32_e32 v87, v38, v84
	v_mul_f32_e32 v86, v39, v84
	v_pk_mul_f32 v[38:39], v[20:21], v[84:85] op_sel_hi:[1,0]
	v_pk_mul_f32 v[20:21], v[6:7], v[84:85] op_sel_hi:[1,0]
	v_pk_mul_f32 v[4:5], v[48:49], v[48:49]
	v_pk_mul_f32 v[22:23], v[22:23], v[84:85] op_sel_hi:[1,0]
	v_pk_mul_f32 v[6:7], v[20:21], v[20:21]
	v_pk_fma_f32 v[4:5], v[38:39], v[38:39], v[4:5]
	v_pk_mul_f32 v[130:131], v[10:11], v[84:85] op_sel_hi:[1,0]
	v_pk_mul_f32 v[132:133], v[8:9], v[84:85] op_sel_hi:[1,0]
	v_pk_fma_f32 v[6:7], v[22:23], v[22:23], v[6:7]
	v_pk_mul_f32 v[26:27], v[26:27], v[84:85] op_sel_hi:[1,0]
	v_pk_mul_f32 v[24:25], v[24:25], v[84:85] op_sel_hi:[1,0]
	v_pk_mul_f32 v[178:179], v[130:131], v[130:131]
	v_mul_f32_e32 v108, v52, v84
	v_mul_f32_e32 v107, v53, v84
	v_pk_fma_f32 v[178:179], v[26:27], v[26:27], v[178:179]
	v_pk_mul_f32 v[12:13], v[12:13], v[84:85] op_sel_hi:[1,0]
	v_pk_mul_f32 v[188:189], v[28:29], v[84:85] op_sel_hi:[1,0]
	v_pk_mul_f32 v[28:29], v[12:13], v[12:13]
	s_waitcnt vmcnt(1)
	v_lshlrev_b32_e32 v72, 16, v70
	v_and_b32_e32 v73, 0xffff0000, v70
	v_lshlrev_b32_e32 v74, 16, v71
	v_and_b32_e32 v75, 0xffff0000, v71
	v_mov_b64_e32 v[70:71], v[190:191]
	v_pk_fma_f32 v[110:111], v[72:73], v[72:73], v[4:5]
	v_pk_mul_f32 v[4:5], v[132:133], v[132:133]
	v_pk_fma_f32 v[52:53], v[74:75], v[74:75], v[6:7]
	v_pk_fma_f32 v[156:157], v[24:25], v[24:25], v[4:5]
	v_add_f32_e32 v40, v110, v111
	v_add_f32_e32 v40, v52, v40
	v_add_f32_e32 v40, v53, v40
	v_pk_fma_f32 v[28:29], v[188:189], v[188:189], v[28:29]
	s_waitcnt vmcnt(0)
	v_lshlrev_b32_e32 v76, 16, v70
	v_and_b32_e32 v77, 0xffff0000, v70
	v_lshlrev_b32_e32 v78, 16, v71
	v_and_b32_e32 v79, 0xffff0000, v71
	v_mov_b64_e32 v[70:71], v[192:193]
	v_pk_fma_f32 v[186:187], v[78:79], v[78:79], v[178:179]
	v_mov_b64_e32 v[68:69], v[194:195]
	v_pk_fma_f32 v[156:157], v[76:77], v[76:77], v[156:157]
	s_waitcnt vmcnt(1)
	v_lshlrev_b32_e32 v82, 16, v71
	v_and_b32_e32 v83, 0xffff0000, v71
	v_pk_fma_f32 v[36:37], v[82:83], v[82:83], v[14:15]
	v_pk_mul_f32 v[14:15], v[30:31], v[30:31]
	v_lshlrev_b32_e32 v80, 16, v70
	v_and_b32_e32 v81, 0xffff0000, v70
	s_waitcnt vmcnt(0)
	v_lshlrev_b32_e32 v70, 16, v68
	v_and_b32_e32 v71, 0xffff0000, v68
	v_pk_fma_f32 v[14:15], v[46:47], v[46:47], v[14:15]
	v_lshlrev_b32_e32 v68, 16, v69
	v_pk_fma_f32 v[32:33], v[70:71], v[70:71], v[14:15]
	v_pk_mul_f32 v[14:15], v[18:19], v[18:19]
	v_and_b32_e32 v69, 0xffff0000, v69
	v_pk_fma_f32 v[14:15], v[50:51], v[50:51], v[14:15]
	v_add_f32_e32 v40, v156, v40
	v_pk_fma_f32 v[34:35], v[68:69], v[68:69], v[14:15]
	global_load_dwordx4 v[14:17], v154, s[10:11]
	global_load_dwordx4 v[8:11], v154, s[10:11] offset:288
	global_load_dwordx4 v[4:7], v154, s[10:11] offset:352
	global_load_dwordx4 v[178:181], v154, s[10:11] offset:64
	global_load_dwordx4 v[182:185], v154, s[10:11] offset:192
	v_add_f32_e32 v40, v157, v40
	v_add_f32_e32 v40, v186, v40
	v_pk_fma_f32 v[28:29], v[80:81], v[80:81], v[28:29]
	v_add_f32_e32 v40, v187, v40
	v_add_f32_e32 v28, v28, v40
	v_add_f32_e32 v28, v29, v28
	v_add_f32_e32 v28, v36, v28
	v_add_f32_e32 v28, v37, v28
	v_add_f32_e32 v28, v32, v28
	v_add_f32_e32 v28, v33, v28
	v_add_f32_e32 v28, v34, v28
	v_add_f32_e32 v28, v35, v28
	ds_bpermute_b32 v29, v155, v28
	s_waitcnt lgkmcnt(0)
	v_add_f32_e32 v28, v28, v29
	v_fmamk_f32 v28, v28, 0x3c2aaaab, v206
	v_cmp_gt_f32_e32 vcc, s30, v28
	v_mul_f32_e32 v29, 0x4b800000, v28
	s_nop 0
	v_cndmask_b32_e32 v28, v28, v29, vcc
	v_rsq_f32_e32 v28, v28
	s_nop 0
	v_mul_f32_e32 v29, 0x45800000, v28
	v_cndmask_b32_e32 v40, v28, v29, vcc
	s_waitcnt vmcnt(4)
	v_pk_mul_f32 v[14:15], v[14:15], v[40:41] op_sel_hi:[1,0]
	s_nop 0
	v_pk_mul_f32 v[34:35], v[38:39], v[14:15]
	v_pk_mul_f32 v[14:15], v[16:17], v[40:41] op_sel_hi:[1,0]
	s_waitcnt vmcnt(3)
; DI uint32_t pack2(float a, float b) { f2_t v = {a, b}; bf2_t r = __builtin_convertvector(v, bf2_t); return __builtin_bit_cast(uint32_t, r); }
; DI u16 f2bf(float x) { return (u16)(pack2(x, 0.f) & 0xffffu); }
; DI int crow(int reg, int h) { return (reg & 3) + 8 * (reg >> 2) + 4 * h; }
; DI void prep_item(const Params& p, int layer, int item, char* smem) {
;     ...
;     for (int g = 0; g < 4; ++g) {
;       float4 g0 = *(const float4*)(gk + 8 * g + 4 * h);
;       float4 g1 = *(const float4*)(gk + 32 + 8 * g + 4 * h);
;       float4 g2 = *(const float4*)(gk + 64 + 8 * g + 4 * h);
;       acc[0][4 * g] *= r2 * g0.x; acc[0][4 * g + 1] *= r2 * g0.y; acc[0][4 * g + 2] *= r2 * g0.z; acc[0][4 * g + 3] *= r2 * g0.w;
;       acc[1][4 * g] *= r2 * g1.x; acc[1][4 * g + 1] *= r2 * g1.y; acc[1][4 * g + 2] *= r2 * g1.z; acc[1][4 * g + 3] *= r2 * g1.w;
;       kpe[4 * g] *= r2 * g2.x; kpe[4 * g + 1] *= r2 * g2.y; kpe[4 * g + 2] *= r2 * g2.z; kpe[4 * g + 3] *= r2 * g2.w;
;     }
; #pragma unroll
;     for (int reg = 0; reg < 8; ++reg) {
;       float x1 = kpe[reg], x2 = kpe[reg + 8];
;       kpe[reg] = x1 * cs[reg] - x2 * sn[reg];
;       kpe[reg + 8] = x2 * cs[reg] + x1 * sn[reg];
;     }
;     u16* ko = KB + ((size_t)(b * 8 + hd) * 4096 + s) * 96;
; #pragma unroll
;     for (int g = 0; g < 4; ++g) {
;       *(uint2*)(ko + 8 * g + 4 * h) = make_uint2(pack2(acc[0][4 * g], acc[0][4 * g + 1]), pack2(acc[0][4 * g + 2], acc[0][4 * g + 3]));
;       *(uint2*)(ko + 32 + 8 * g + 4 * h) = make_uint2(pack2(acc[1][4 * g], acc[1][4 * g + 1]), pack2(acc[1][4 * g + 2], acc[1][4 * g + 3]));
;       *(uint2*)(ko + 64 + 8 * g + 4 * h) = make_uint2(pack2(kpe[4 * g], kpe[4 * g + 1]), pack2(kpe[4 * g + 2], kpe[4 * g + 3]));
;     }
; #pragma unroll
;     for (int nt = 2; nt < 4; ++nt)
; #pragma unroll
;       for (int i = 0; i < 16; ++i) {
;         const int d = (nt - 2) * 32 + crow(i, h);
;         VTB[((size_t)((b * 8 + hd) * 64 + d)) * 4096 + s] = f2bf(acc[nt][i]);
	v_pk_mul_f32 v[8:9], v[40:41], v[8:9] op_sel_hi:[0,1]
	v_pk_mul_f32 v[38:39], v[22:23], v[14:15]
	v_pk_mul_f32 v[14:15], v[42:43], v[40:41] op_sel_hi:[1,0]
	v_pk_mul_f32 v[52:53], v[8:9], v[76:77]
	v_pk_mul_f32 v[32:33], v[48:49], v[14:15]
	v_pk_mul_f32 v[14:15], v[44:45], v[40:41] op_sel_hi:[1,0]
	v_pk_mul_f32 v[8:9], v[40:41], v[10:11] op_sel_hi:[0,1]
	v_pk_mul_f32 v[36:37], v[20:21], v[14:15]
	v_pk_mul_f32 v[14:15], v[162:163], v[40:41] op_sel_hi:[1,0]
	v_pk_mul_f32 v[48:49], v[8:9], v[78:79]
	v_pk_mul_f32 v[44:45], v[14:15], v[72:73]
	v_pk_mul_f32 v[14:15], v[164:165], v[40:41] op_sel_hi:[1,0]
	s_waitcnt vmcnt(1)
	v_pk_mul_f32 v[8:9], v[40:41], v[178:179] op_sel_hi:[0,1]
	v_pk_mul_f32 v[42:43], v[14:15], v[74:75]
	v_pk_mul_f32 v[14:15], v[170:171], v[40:41] op_sel_hi:[1,0]
	v_pk_mul_f32 v[4:5], v[40:41], v[4:5] op_sel_hi:[0,1]
	v_pk_mul_f32 v[24:25], v[24:25], v[14:15]
	v_pk_mul_f32 v[14:15], v[172:173], v[40:41] op_sel_hi:[1,0]
	v_pk_mul_f32 v[4:5], v[4:5], v[70:71]
	v_pk_mul_f32 v[28:29], v[26:27], v[14:15]
	v_pk_mul_f32 v[14:15], v[174:175], v[40:41] op_sel_hi:[1,0]
	v_pk_mul_f32 v[6:7], v[40:41], v[6:7] op_sel_hi:[0,1]
	v_pk_mul_f32 v[22:23], v[132:133], v[14:15]
	v_pk_mul_f32 v[14:15], v[176:177], v[40:41] op_sel_hi:[1,0]
	v_pk_mul_f32 v[6:7], v[6:7], v[68:69]
	v_pk_mul_f32 v[26:27], v[130:131], v[14:15]
	v_pk_mul_f32 v[14:15], v[188:189], v[8:9]
	v_pk_mul_f32 v[8:9], v[40:41], v[180:181] op_sel_hi:[0,1]
	v_pk_mul_f32 v[20:21], v[56:57], v[8:9]
	s_waitcnt vmcnt(0)
	v_pk_mul_f32 v[8:9], v[40:41], v[182:183] op_sel_hi:[0,1]
	v_pk_mul_f32 v[12:13], v[12:13], v[8:9]
	v_pk_mul_f32 v[8:9], v[40:41], v[184:185] op_sel_hi:[0,1]
	v_pk_mul_f32 v[16:17], v[54:55], v[8:9]
	v_pk_mul_f32 v[8:9], v[40:41], v[166:167] op_sel_hi:[0,1]
	v_pk_mul_f32 v[56:57], v[8:9], v[80:81]
	v_pk_mul_f32 v[8:9], v[40:41], v[168:169] op_sel_hi:[0,1]
	v_pk_mul_f32 v[54:55], v[8:9], v[82:83]
	global_load_dwordx4 v[8:11], v154, s[10:11] offset:96
	v_cvt_pk_bf16_f32 v12, v12, v13
	v_cvt_pk_bf16_f32 v13, v16, v17
	v_cvt_pk_bf16_f32 v34, v34, v35
	v_cvt_pk_bf16_f32 v35, v38, v39
	v_cvt_pk_bf16_f32 v32, v32, v33
	v_cvt_pk_bf16_f32 v33, v36, v37
	v_cvt_pk_bf16_f32 v14, v14, v15
	v_cvt_pk_bf16_f32 v15, v20, v21
	s_waitcnt vmcnt(0)
	v_pk_mul_f32 v[8:9], v[40:41], v[8:9] op_sel_hi:[0,1]
	v_pk_mul_f32 v[46:47], v[46:47], v[8:9]
	v_pk_mul_f32 v[8:9], v[40:41], v[10:11] op_sel_hi:[0,1]
	v_pk_mul_f32 v[50:51], v[50:51], v[8:9]
	global_load_dwordx4 v[8:11], v154, s[10:11] offset:224
	s_waitcnt vmcnt(0)
	v_pk_mul_f32 v[8:9], v[40:41], v[8:9] op_sel_hi:[0,1]
	v_pk_mul_f32 v[10:11], v[40:41], v[10:11] op_sel_hi:[0,1]
	v_pk_mul_f32 v[8:9], v[30:31], v[8:9]
	v_pk_mul_f32 v[10:11], v[18:19], v[10:11]
	v_pk_mul_f32 v[18:19], v[116:117], v[56:57]
	v_pk_mul_f32 v[30:31], v[118:119], v[56:57]
	v_pk_fma_f32 v[18:19], v[118:119], v[44:45], v[18:19] neg_lo:[0,0,1] neg_hi:[0,0,1]
	v_pk_fma_f32 v[30:31], v[116:117], v[44:45], v[30:31]
	v_pk_mul_f32 v[44:45], v[120:121], v[54:55]
	v_pk_mul_f32 v[54:55], v[122:123], v[54:55]
	v_pk_fma_f32 v[44:45], v[122:123], v[42:43], v[44:45] neg_lo:[0,0,1] neg_hi:[0,0,1]
	v_pk_fma_f32 v[42:43], v[120:121], v[42:43], v[54:55]
	v_pk_mul_f32 v[54:55], v[124:125], v[4:5]
	v_pk_mul_f32 v[4:5], v[126:127], v[4:5]
	v_pk_fma_f32 v[54:55], v[126:127], v[52:53], v[54:55] neg_lo:[0,0,1] neg_hi:[0,0,1]
	v_pk_fma_f32 v[4:5], v[124:125], v[52:53], v[4:5]
	v_pk_mul_f32 v[52:53], v[150:151], v[6:7]
	v_pk_mul_f32 v[6:7], v[152:153], v[6:7]
	v_pk_fma_f32 v[52:53], v[152:153], v[48:49], v[52:53] neg_lo:[0,0,1] neg_hi:[0,0,1]
	v_pk_fma_f32 v[6:7], v[150:151], v[48:49], v[6:7]
	v_mov_b64_e32 v[48:49], s[18:19]
	v_mad_u64_u32 v[48:49], s[18:19], v98, s13, v[48:49]
	v_cvt_pk_bf16_f32 v8, v8, v9
	v_cvt_pk_bf16_f32 v9, v10, v11
	v_lshl_or_b32 v10, s12, 6, v96
	v_mad_i32_i24 v49, s15, v212, v49
	v_cvt_pk_bf16_f32 v4, v4, v5
	v_cvt_pk_bf16_f32 v5, v6, v7
	v_subrev_u32_e32 v6, 64, v10
	v_readlane_b32 s12, v252, 12
	v_lshl_add_u64 v[48:49], v[48:49], 0, v[2:3]
	v_lshlrev_b32_e32 v2, 1, v97
	v_readlane_b32 s13, v252, 13
	v_ashrrev_i32_e32 v7, 31, v6
	v_cvt_pk_bf16_f32 v18, v18, v19
	v_cvt_pk_bf16_f32 v19, v44, v45
	global_store_dwordx2 v[48:49], v[4:5], off offset:176
	v_lshl_add_u64 v[4:5], s[12:13], 0, v[2:3]
	v_lshlrev_b64 v[6:7], 13, v[6:7]
	global_store_dwordx2 v[48:49], v[18:19], off offset:128
	v_cvt_pk_bf16_f32 v18, v24, v25
	v_cvt_pk_bf16_f32 v19, v28, v29
	v_lshl_add_u64 v[6:7], v[4:5], 0, v[6:7]
	global_store_dwordx2 v[48:49], v[18:19], off offset:16
	v_cvt_pk_bf16_f32 v18, v22, v23
	v_cvt_pk_bf16_f32 v19, v26, v27
	global_store_dwordx2 v[48:49], v[12:13], off offset:96
	v_cvt_pk_bf16_f32 v12, v30, v31
	v_cvt_pk_bf16_f32 v13, v42, v43
	global_store_dwordx2 v[48:49], v[8:9], off offset:112
	v_add_co_u32_e32 v8, vcc, s5, v6
	global_store_dwordx2 v[48:49], v[18:19], off offset:80
	v_cvt_pk_bf16_f32 v18, v54, v55
	v_cvt_pk_bf16_f32 v19, v52, v53
	global_store_dwordx2 v[48:49], v[12:13], off offset:160
	v_cvt_pk_bf16_f32 v12, v46, v47
	v_cvt_pk_bf16_f32 v13, v50, v51
	v_cvt_pk_bf16_f32 v2, v108, s0
	v_addc_co_u32_e32 v9, vcc, 0, v7, vcc
	global_store_dwordx2 v[48:49], v[34:35], off
	global_store_dwordx2 v[48:49], v[32:33], off offset:64
	global_store_dwordx2 v[48:49], v[18:19], off offset:144
	global_store_dwordx2 v[48:49], v[14:15], off offset:32
	global_store_dwordx2 v[48:49], v[12:13], off offset:48
	global_store_short v[8:9], v2, off
	v_or_b32_e32 v8, 1, v10
	v_ashrrev_i32_e32 v9, 31, v8
	v_lshlrev_b64 v[8:9], 13, v[8:9]
	v_cvt_pk_bf16_f32 v2, v107, s0
	v_lshl_add_u64 v[8:9], v[4:5], 0, v[8:9]
	global_store_short v[8:9], v2, off
	v_or_b32_e32 v8, 2, v10
	v_ashrrev_i32_e32 v9, 31, v8
; DI u16 f2bf(float x) { return (u16)(pack2(x, 0.f) & 0xffffu); }
; DI int crow(int reg, int h) { return (reg & 3) + 8 * (reg >> 2) + 4 * h; }
; DI void prep_item(const Params& p, int layer, int item, char* smem) {
;     ...
; #pragma unroll
;     for (int nt = 2; nt < 4; ++nt)
; #pragma unroll
;       for (int i = 0; i < 16; ++i) {
;         const int d = (nt - 2) * 32 + crow(i, h);
;         VTB[((size_t)((b * 8 + hd) * 64 + d)) * 4096 + s] = f2bf(acc[nt][i]);
;       }
;   }
;   __syncthreads();
;   {
;     const u16* qp = prow + O_DSQ + hd * 64 + 32 * h;
;     u16* qo = (u16*)(p.ws + WS_DSQ) + ((size_t)token * 8 + hd) * 64 + 32 * h;
	v_lshlrev_b64 v[8:9], 13, v[8:9]
	v_cvt_pk_bf16_f32 v2, v106, s0
	v_lshl_add_u64 v[8:9], v[4:5], 0, v[8:9]
	global_store_short v[8:9], v2, off
	v_or_b32_e32 v8, 3, v10
	v_ashrrev_i32_e32 v9, 31, v8
	v_lshlrev_b64 v[8:9], 13, v[8:9]
	v_cvt_pk_bf16_f32 v2, v105, s0
	v_lshl_add_u64 v[8:9], v[4:5], 0, v[8:9]
	global_store_short v[8:9], v2, off
	v_or_b32_e32 v8, 8, v10
	v_ashrrev_i32_e32 v9, 31, v8
	v_lshlrev_b64 v[8:9], 13, v[8:9]
	v_cvt_pk_bf16_f32 v2, v104, s0
	v_lshl_add_u64 v[8:9], v[4:5], 0, v[8:9]
	global_store_short v[8:9], v2, off
	v_or_b32_e32 v8, 9, v10
	v_ashrrev_i32_e32 v9, 31, v8
	v_lshlrev_b64 v[8:9], 13, v[8:9]
	v_cvt_pk_bf16_f32 v2, v103, s0
	v_lshl_add_u64 v[8:9], v[4:5], 0, v[8:9]
	global_store_short v[8:9], v2, off
	v_or_b32_e32 v8, 10, v10
	v_ashrrev_i32_e32 v9, 31, v8
	v_lshlrev_b64 v[8:9], 13, v[8:9]
	v_cvt_pk_bf16_f32 v2, v102, s0
	v_lshl_add_u64 v[8:9], v[4:5], 0, v[8:9]
	global_store_short v[8:9], v2, off
	v_or_b32_e32 v8, 11, v10
	v_ashrrev_i32_e32 v9, 31, v8
	v_lshlrev_b64 v[8:9], 13, v[8:9]
	v_cvt_pk_bf16_f32 v2, v101, s0
	v_lshl_add_u64 v[8:9], v[4:5], 0, v[8:9]
	global_store_short v[8:9], v2, off
	v_or_b32_e32 v8, 16, v10
	v_ashrrev_i32_e32 v9, 31, v8
	v_lshlrev_b64 v[8:9], 13, v[8:9]
	v_cvt_pk_bf16_f32 v2, v100, s0
	v_lshl_add_u64 v[8:9], v[4:5], 0, v[8:9]
	global_store_short v[8:9], v2, off
	v_or_b32_e32 v8, 17, v10
	v_ashrrev_i32_e32 v9, 31, v8
	v_lshlrev_b64 v[8:9], 13, v[8:9]
	v_cvt_pk_bf16_f32 v2, v99, s0
	v_lshl_add_u64 v[8:9], v[4:5], 0, v[8:9]
	global_store_short v[8:9], v2, off
	v_or_b32_e32 v8, 18, v10
	v_ashrrev_i32_e32 v9, 31, v8
	v_lshlrev_b64 v[8:9], 13, v[8:9]
	v_cvt_pk_bf16_f32 v2, v95, s0
	v_lshl_add_u64 v[8:9], v[4:5], 0, v[8:9]
	global_store_short v[8:9], v2, off
	v_or_b32_e32 v8, 19, v10
	v_ashrrev_i32_e32 v9, 31, v8
	v_lshlrev_b64 v[8:9], 13, v[8:9]
	v_cvt_pk_bf16_f32 v2, v94, s0
	v_lshl_add_u64 v[8:9], v[4:5], 0, v[8:9]
	global_store_short v[8:9], v2, off
	v_or_b32_e32 v8, 24, v10
	v_ashrrev_i32_e32 v9, 31, v8
	v_lshlrev_b64 v[8:9], 13, v[8:9]
	v_cvt_pk_bf16_f32 v2, v93, s0
	v_lshl_add_u64 v[8:9], v[4:5], 0, v[8:9]
	global_store_short v[8:9], v2, off
	v_or_b32_e32 v8, 25, v10
	v_ashrrev_i32_e32 v9, 31, v8
	v_lshlrev_b64 v[8:9], 13, v[8:9]
	v_cvt_pk_bf16_f32 v2, v92, s0
	v_lshl_add_u64 v[8:9], v[4:5], 0, v[8:9]
	global_store_short v[8:9], v2, off
	v_or_b32_e32 v8, 26, v10
	v_ashrrev_i32_e32 v9, 31, v8
	v_lshlrev_b64 v[8:9], 13, v[8:9]
	v_cvt_pk_bf16_f32 v2, v91, s0
	v_lshl_add_u64 v[8:9], v[4:5], 0, v[8:9]
	global_store_short v[8:9], v2, off
	v_or_b32_e32 v8, 27, v10
	v_ashrrev_i32_e32 v9, 31, v8
	v_lshlrev_b64 v[8:9], 13, v[8:9]
	s_mov_b32 s5, 0xc0000
	v_cvt_pk_bf16_f32 v2, v90, s0
	v_lshl_add_u64 v[8:9], v[4:5], 0, v[8:9]
	v_add_co_u32_e32 v6, vcc, s5, v6
	global_store_short v[8:9], v2, off
	v_cvt_pk_bf16_f32 v2, v89, s0
	v_addc_co_u32_e32 v7, vcc, 0, v7, vcc
	global_store_short v[6:7], v2, off
	v_or_b32_e32 v6, 33, v10
	v_ashrrev_i32_e32 v7, 31, v6
	v_lshlrev_b64 v[6:7], 13, v[6:7]
	v_cvt_pk_bf16_f32 v2, v88, s0
	v_lshl_add_u64 v[6:7], v[4:5], 0, v[6:7]
	global_store_short v[6:7], v2, off
	v_or_b32_e32 v6, 34, v10
	v_ashrrev_i32_e32 v7, 31, v6
	v_lshlrev_b64 v[6:7], 13, v[6:7]
	v_cvt_pk_bf16_f32 v2, v87, s0
	v_lshl_add_u64 v[6:7], v[4:5], 0, v[6:7]
	global_store_short v[6:7], v2, off
	v_or_b32_e32 v6, 35, v10
	v_ashrrev_i32_e32 v7, 31, v6
	v_lshlrev_b64 v[6:7], 13, v[6:7]
	v_cvt_pk_bf16_f32 v2, v86, s0
	v_lshl_add_u64 v[6:7], v[4:5], 0, v[6:7]
	global_store_short v[6:7], v2, off
	v_or_b32_e32 v6, 40, v10
	v_ashrrev_i32_e32 v7, 31, v6
	v_lshlrev_b64 v[6:7], 13, v[6:7]
	v_cvt_pk_bf16_f32 v2, v85, s0
	v_lshl_add_u64 v[6:7], v[4:5], 0, v[6:7]
	global_store_short v[6:7], v2, off
	v_or_b32_e32 v6, 41, v10
	v_ashrrev_i32_e32 v7, 31, v6
	v_lshlrev_b64 v[6:7], 13, v[6:7]
	v_cvt_pk_bf16_f32 v2, v67, s0
	v_lshl_add_u64 v[6:7], v[4:5], 0, v[6:7]
	global_store_short v[6:7], v2, off
	v_or_b32_e32 v6, 42, v10
	v_ashrrev_i32_e32 v7, 31, v6
	v_lshlrev_b64 v[6:7], 13, v[6:7]
	v_cvt_pk_bf16_f32 v2, v66, s0
	v_lshl_add_u64 v[6:7], v[4:5], 0, v[6:7]
	global_store_short v[6:7], v2, off
	v_or_b32_e32 v6, 43, v10
	v_ashrrev_i32_e32 v7, 31, v6
	v_lshlrev_b64 v[6:7], 13, v[6:7]
	v_cvt_pk_bf16_f32 v2, v65, s0
	v_lshl_add_u64 v[6:7], v[4:5], 0, v[6:7]
	global_store_short v[6:7], v2, off
	v_or_b32_e32 v6, 48, v10
	v_ashrrev_i32_e32 v7, 31, v6
	v_lshlrev_b64 v[6:7], 13, v[6:7]
	v_cvt_pk_bf16_f32 v2, v64, s0
	v_lshl_add_u64 v[6:7], v[4:5], 0, v[6:7]
	global_store_short v[6:7], v2, off
	v_or_b32_e32 v6, 49, v10
	v_ashrrev_i32_e32 v7, 31, v6
	v_lshlrev_b64 v[6:7], 13, v[6:7]
	v_cvt_pk_bf16_f32 v2, v63, s0
	v_lshl_add_u64 v[6:7], v[4:5], 0, v[6:7]
	global_store_short v[6:7], v2, off
	v_or_b32_e32 v6, 50, v10
	v_ashrrev_i32_e32 v7, 31, v6
	v_lshlrev_b64 v[6:7], 13, v[6:7]
	v_cvt_pk_bf16_f32 v2, v62, s0
	v_lshl_add_u64 v[6:7], v[4:5], 0, v[6:7]
	global_store_short v[6:7], v2, off
	v_or_b32_e32 v6, 51, v10
	v_ashrrev_i32_e32 v7, 31, v6
	v_lshlrev_b64 v[6:7], 13, v[6:7]
	v_cvt_pk_bf16_f32 v2, v61, s0
	v_lshl_add_u64 v[6:7], v[4:5], 0, v[6:7]
	global_store_short v[6:7], v2, off
	v_or_b32_e32 v6, 56, v10
	v_ashrrev_i32_e32 v7, 31, v6
	v_lshlrev_b64 v[6:7], 13, v[6:7]
	v_cvt_pk_bf16_f32 v2, v60, s0
	v_lshl_add_u64 v[6:7], v[4:5], 0, v[6:7]
	global_store_short v[6:7], v2, off
	v_or_b32_e32 v6, 57, v10
	v_ashrrev_i32_e32 v7, 31, v6
	v_lshlrev_b64 v[6:7], 13, v[6:7]
	v_cvt_pk_bf16_f32 v2, v59, s0
	v_lshl_add_u64 v[6:7], v[4:5], 0, v[6:7]
	global_store_short v[6:7], v2, off
	v_or_b32_e32 v6, 58, v10
	v_ashrrev_i32_e32 v7, 31, v6
	v_lshlrev_b64 v[6:7], 13, v[6:7]
	v_cvt_pk_bf16_f32 v2, v58, s0
	v_lshl_add_u64 v[6:7], v[4:5], 0, v[6:7]
	global_store_short v[6:7], v2, off
	v_or_b32_e32 v6, 59, v10
	v_ashrrev_i32_e32 v7, 31, v6
	v_lshlrev_b64 v[6:7], 13, v[6:7]
	v_cvt_pk_bf16_f32 v2, v41, s0
	v_lshl_add_u64 v[4:5], v[4:5], 0, v[6:7]
	global_store_short v[4:5], v2, off
	v_and_b32_e32 v4, 32, v159
	v_lshl_add_u64 v[6:7], v[114:115], 0, s[16:17]
	v_lshlrev_b32_e32 v2, 1, v4
	v_readlane_b32 s12, v252, 20
	v_lshl_add_u64 v[14:15], v[6:7], 0, v[2:3]
	v_lshlrev_b64 v[6:7], 10, v[0:1]
	v_readlane_b32 s13, v252, 21
	s_barrier
; DI uint32_t pack2(float a, float b) { f2_t v = {a, b}; bf2_t r = __builtin_convertvector(v, bf2_t); return __builtin_bit_cast(uint32_t, r); }
; DI float bflo(uint32_t u) { return __uint_as_float(u << 16); }
; DI float bfhi(uint32_t u) { return __uint_as_float(u & 0xffff0000u); }
; DI float xor32(float v) { return __shfl_xor(v, 32); }
; DI void prep_item(const Params& p, int layer, int item, char* smem) {
;     ...
;   {
;     const u16* qp = prow + O_DSQ + hd * 64 + 32 * h;
;     u16* qo = (u16*)(p.ws + WS_DSQ) + ((size_t)token * 8 + hd) * 64 + 32 * h;
;     uint4 u[4];
;     float f[32];
;     float ss = 0.f;
; #pragma unroll
;     for (int i = 0; i < 4; ++i) {
;       u[i] = *(const uint4*)(qp + 8 * i);
;       f[8 * i] = bflo(u[i].x); f[8 * i + 1] = bfhi(u[i].x); f[8 * i + 2] = bflo(u[i].y); f[8 * i + 3] = bfhi(u[i].y);
;       f[8 * i + 4] = bflo(u[i].z); f[8 * i + 5] = bfhi(u[i].z); f[8 * i + 6] = bflo(u[i].w); f[8 * i + 7] = bfhi(u[i].w);
;     }
; #pragma unroll
;     for (int i = 0; i < 32; ++i) ss += f[i] * f[i];
;     ss += xor32(ss);
;     const float rr = rsqrtf(ss * (1.f / 64.f) + EPS) * C_SB;
;     const float* gq = p.dsa_q_g + layer * 64 + 32 * h;
; #pragma unroll
;     for (int i = 0; i < 4; ++i) {
;       float4 ga = *(const float4*)(gq + 8 * i), gb = *(const float4*)(gq + 8 * i + 4);
;       *(uint4*)(qo + 8 * i) = make_uint4(pack2(f[8 * i] * rr * ga.x, f[8 * i + 1] * rr * ga.y), pack2(f[8 * i + 2] * rr * ga.z, f[8 * i + 3] * rr * ga.w),
;                                          pack2(f[8 * i + 4] * rr * gb.x, f[8 * i + 5] * rr * gb.y), pack2(f[8 * i + 6] * rr * gb.z, f[8 * i + 7] * rr * gb.w));
;     }
	s_nop 0
	v_lshl_add_u64 v[6:7], s[12:13], 0, v[6:7]
	v_lshl_add_u64 v[44:45], v[6:7], 0, s[16:17]
	global_load_dwordx4 v[40:43], v[14:15], off offset:816
	global_load_dwordx4 v[6:9], v[14:15], off offset:800
	global_load_dwordx4 v[10:13], v[14:15], off offset:784
	s_nop 0
	global_load_dwordx4 v[14:17], v[14:15], off offset:768
	v_lshlrev_b32_e32 v5, 2, v4
	s_mov_b32 s5, 0x800000
	s_mov_b64 s[12:13], -1
	s_waitcnt vmcnt(2)
	v_lshlrev_b32_e32 v22, 16, v6
	s_waitcnt vmcnt(1)
	v_lshlrev_b32_e32 v30, 16, v10
	s_waitcnt vmcnt(0)
	v_lshlrev_b32_e32 v38, 16, v14
	v_and_b32_e32 v39, 0xffff0000, v14
	v_lshlrev_b32_e32 v36, 16, v15
	v_and_b32_e32 v37, 0xffff0000, v15
	v_lshlrev_b32_e32 v34, 16, v16
	v_and_b32_e32 v35, 0xffff0000, v16
	v_lshlrev_b32_e32 v32, 16, v17
	v_and_b32_e32 v33, 0xffff0000, v17
	v_and_b32_e32 v31, 0xffff0000, v10
	v_lshlrev_b32_e32 v28, 16, v11
	v_and_b32_e32 v29, 0xffff0000, v11
	v_lshlrev_b32_e32 v26, 16, v12
	v_and_b32_e32 v27, 0xffff0000, v12
	v_lshlrev_b32_e32 v24, 16, v13
	v_and_b32_e32 v25, 0xffff0000, v13
	v_and_b32_e32 v23, 0xffff0000, v6
	v_lshlrev_b32_e32 v20, 16, v7
	v_and_b32_e32 v21, 0xffff0000, v7
	v_lshlrev_b32_e32 v18, 16, v8
	v_and_b32_e32 v19, 0xffff0000, v8
	v_lshlrev_b32_e32 v16, 16, v9
	v_and_b32_e32 v17, 0xffff0000, v9
	v_lshlrev_b32_e32 v14, 16, v40
	v_and_b32_e32 v15, 0xffff0000, v40
	v_lshlrev_b32_e32 v12, 16, v41
	v_and_b32_e32 v13, 0xffff0000, v41
	v_lshlrev_b32_e32 v11, 16, v42
	v_and_b32_e32 v10, 0xffff0000, v42
	v_lshlrev_b32_e32 v9, 16, v43
	v_and_b32_e32 v8, 0xffff0000, v43
	v_lshl_add_u64 v[6:7], v[44:45], 0, v[2:3]
	global_load_dwordx4 v[40:43], v5, s[6:7] offset:16
	global_load_dwordx4 v[44:47], v5, s[6:7]
	global_load_dwordx4 v[96:99], v5, s[6:7] offset:48
	global_load_dwordx4 v[100:103], v5, s[6:7] offset:32
	global_load_dwordx4 v[104:107], v5, s[6:7] offset:80
	global_load_dwordx4 v[108:111], v5, s[6:7] offset:64
	global_load_dwordx4 v[116:119], v5, s[6:7] offset:112
	global_load_dwordx4 v[120:123], v5, s[6:7] offset:96
	v_pk_mul_f32 v[58:59], v[38:39], v[38:39]
	v_pk_mul_f32 v[56:57], v[36:37], v[36:37]
	v_add_f32_e32 v2, v58, v59
	v_add_f32_e32 v2, v2, v56
	v_pk_mul_f32 v[54:55], v[34:35], v[34:35]
	v_add_f32_e32 v2, v57, v2
	v_add_f32_e32 v2, v54, v2
	v_pk_mul_f32 v[52:53], v[32:33], v[32:33]
	v_add_f32_e32 v2, v55, v2
	v_add_f32_e32 v2, v52, v2
	v_pk_mul_f32 v[66:67], v[30:31], v[30:31]
	v_add_f32_e32 v2, v53, v2
	v_add_f32_e32 v2, v66, v2
	v_pk_mul_f32 v[64:65], v[28:29], v[28:29]
	v_add_f32_e32 v2, v67, v2
	v_add_f32_e32 v2, v64, v2
	v_pk_mul_f32 v[62:63], v[26:27], v[26:27]
	v_add_f32_e32 v2, v65, v2
	v_add_f32_e32 v2, v62, v2
	v_pk_mul_f32 v[60:61], v[24:25], v[24:25]
	v_add_f32_e32 v2, v63, v2
	v_add_f32_e32 v2, v60, v2
	v_pk_mul_f32 v[74:75], v[22:23], v[22:23]
	v_add_f32_e32 v2, v61, v2
	v_add_f32_e32 v2, v74, v2
	v_pk_mul_f32 v[72:73], v[20:21], v[20:21]
	v_add_f32_e32 v2, v75, v2
	v_add_f32_e32 v2, v72, v2
	v_pk_mul_f32 v[70:71], v[18:19], v[18:19]
	v_add_f32_e32 v2, v73, v2
	v_add_f32_e32 v2, v70, v2
	v_pk_mul_f32 v[68:69], v[16:17], v[16:17]
	v_add_f32_e32 v2, v71, v2
	v_add_f32_e32 v2, v68, v2
	v_pk_mul_f32 v[78:79], v[14:15], v[14:15]
	v_add_f32_e32 v2, v69, v2
	v_add_f32_e32 v2, v78, v2
	v_pk_mul_f32 v[76:77], v[12:13], v[12:13]
	v_add_f32_e32 v2, v79, v2
	v_add_f32_e32 v2, v76, v2
	v_pk_mul_f32 v[48:49], v[10:11], v[10:11]
	v_add_f32_e32 v2, v77, v2
	v_add_f32_e32 v2, v49, v2
	v_pk_mul_f32 v[50:51], v[8:9], v[8:9]
	v_add_f32_e32 v2, v48, v2
	v_add_f32_e32 v2, v51, v2
	v_add_f32_e32 v2, v50, v2
	ds_bpermute_b32 v48, v155, v2
	s_waitcnt lgkmcnt(0)
	v_add_f32_e32 v2, v2, v48
	v_fmamk_f32 v2, v2, 0x3c800000, v206
	v_cmp_gt_f32_e32 vcc, s30, v2
	v_mul_f32_e32 v48, 0x4b800000, v2
	s_nop 0
	v_cndmask_b32_e32 v2, v2, v48, vcc
	v_rsq_f32_e32 v2, v2
	s_nop 0
	v_mul_f32_e32 v48, 0x45800000, v2
	v_cndmask_b32_e32 v2, v2, v48, vcc
	v_mul_f32_e32 v2, 0x3e38aa3b, v2
	v_pk_mul_f32 v[38:39], v[2:3], v[38:39] op_sel_hi:[0,1]
	v_pk_mul_f32 v[36:37], v[2:3], v[36:37] op_sel_hi:[0,1]
	v_pk_mul_f32 v[34:35], v[2:3], v[34:35] op_sel_hi:[0,1]
	v_pk_mul_f32 v[32:33], v[2:3], v[32:33] op_sel_hi:[0,1]
	v_pk_mul_f32 v[30:31], v[2:3], v[30:31] op_sel_hi:[0,1]
	v_pk_mul_f32 v[28:29], v[2:3], v[28:29] op_sel_hi:[0,1]
	v_pk_mul_f32 v[26:27], v[2:3], v[26:27] op_sel_hi:[0,1]
	v_pk_mul_f32 v[24:25], v[2:3], v[24:25] op_sel_hi:[0,1]
	v_pk_mul_f32 v[22:23], v[2:3], v[22:23] op_sel_hi:[0,1]
	v_pk_mul_f32 v[20:21], v[2:3], v[20:21] op_sel_hi:[0,1]
	v_pk_mul_f32 v[18:19], v[2:3], v[18:19] op_sel_hi:[0,1]
	v_pk_mul_f32 v[16:17], v[2:3], v[16:17] op_sel_hi:[0,1]
	v_pk_mul_f32 v[14:15], v[2:3], v[14:15] op_sel_hi:[0,1]
	s_waitcnt vmcnt(1)
	v_pk_mul_f32 v[34:35], v[40:41], v[34:35]
	s_waitcnt vmcnt(0)
	v_pk_mul_f32 v[38:39], v[44:45], v[38:39]
	v_pk_mul_f32 v[36:37], v[46:47], v[36:37]
	v_pk_mul_f32 v[32:33], v[42:43], v[32:33]
	v_cvt_pk_bf16_f32 v38, v38, v39
	v_cvt_pk_bf16_f32 v39, v36, v37
	v_cvt_pk_bf16_f32 v40, v34, v35
	v_cvt_pk_bf16_f32 v41, v32, v33
	global_store_dwordx4 v[6:7], v[38:41], off
	v_mov_b64_e32 v[32:33], v[96:97]
	v_mov_b64_e32 v[34:35], v[98:99]
	s_nop 0
	v_mov_b64_e32 v[36:37], v[100:101]
	v_mov_b64_e32 v[38:39], v[102:103]
	v_pk_mul_f32 v[12:13], v[2:3], v[12:13] op_sel_hi:[0,1]
	v_pk_mul_f32 v[10:11], v[2:3], v[10:11] op_sel_hi:[0,1]
	v_pk_mul_f32 v[8:9], v[2:3], v[8:9] op_sel_hi:[0,1]
	v_pk_mul_f32 v[26:27], v[32:33], v[26:27]
	v_pk_mul_f32 v[30:31], v[36:37], v[30:31]
	v_pk_mul_f32 v[28:29], v[38:39], v[28:29]
	v_pk_mul_f32 v[24:25], v[34:35], v[24:25]
	v_cvt_pk_bf16_f32 v30, v30, v31
	v_cvt_pk_bf16_f32 v31, v28, v29
	v_cvt_pk_bf16_f32 v32, v26, v27
	v_cvt_pk_bf16_f32 v33, v24, v25
	global_store_dwordx4 v[6:7], v[30:33], off offset:16
	v_mov_b64_e32 v[24:25], v[104:105]
	v_mov_b64_e32 v[26:27], v[106:107]
	s_nop 0
	v_mov_b64_e32 v[28:29], v[108:109]
	v_mov_b64_e32 v[30:31], v[110:111]
	v_pk_mul_f32 v[18:19], v[18:19], v[24:25]
	v_pk_mul_f32 v[22:23], v[28:29], v[22:23]
	v_pk_mul_f32 v[20:21], v[30:31], v[20:21]
	v_pk_mul_f32 v[16:17], v[16:17], v[26:27]
	v_cvt_pk_bf16_f32 v22, v22, v23
	v_cvt_pk_bf16_f32 v23, v20, v21
	v_cvt_pk_bf16_f32 v24, v18, v19
	v_cvt_pk_bf16_f32 v25, v16, v17
	global_store_dwordx4 v[6:7], v[22:25], off offset:32
	v_mov_b64_e32 v[16:17], v[116:117]
	v_mov_b64_e32 v[18:19], v[118:119]
	s_nop 0
	v_mov_b64_e32 v[20:21], v[120:121]
	v_mov_b64_e32 v[22:23], v[122:123]
	v_pk_mul_f32 v[10:11], v[10:11], v[16:17] op_sel:[1,0] op_sel_hi:[0,1]
	v_pk_mul_f32 v[14:15], v[14:15], v[20:21]
	v_pk_mul_f32 v[12:13], v[12:13], v[22:23]
	v_pk_mul_f32 v[8:9], v[8:9], v[18:19] op_sel:[1,0] op_sel_hi:[0,1]
	v_cvt_pk_bf16_f32 v14, v14, v15
	v_cvt_pk_bf16_f32 v15, v12, v13
	v_cvt_pk_bf16_f32 v16, v10, v11
	v_cvt_pk_bf16_f32 v17, v8, v9
	global_store_dwordx4 v[6:7], v[14:17], off offset:48
	s_cbranch_scc1 .LBB0_355
; DI void prep_item(const Params& p, int layer, int item, char* smem) {
;     ...
;   if (hd == 1) {
;     int pm = p.pos[token];
; #pragma unroll
;     for (int off = 1; off < 32; off <<= 1) { const int o = __shfl_xor(pm, off); pm = pm > o ? pm : o; }
;     if (lane == 0) ((int*)(p.ws + WS_PMAX))[tg] = pm;
;   }
	s_cmp_lg_u32 s1, 1
	s_cbranch_scc1 .LBB0_354
	global_load_dword v2, v[112:113], off
	v_xor_b32_e32 v5, 1, v213
	v_cmp_lt_i32_e32 vcc, v5, v160
	s_nop 1
	v_cndmask_b32_e32 v5, v213, v5, vcc
	v_lshlrev_b32_e32 v5, 2, v5
	s_waitcnt vmcnt(0)
	ds_bpermute_b32 v5, v5, v2
	s_waitcnt lgkmcnt(0)
	v_max_i32_e32 v2, v2, v5
	v_xor_b32_e32 v5, 2, v213
	v_cmp_lt_i32_e32 vcc, v5, v160
	s_nop 1
	v_cndmask_b32_e32 v5, v213, v5, vcc
	v_lshlrev_b32_e32 v5, 2, v5
	ds_bpermute_b32 v5, v5, v2
	s_waitcnt lgkmcnt(0)
	v_max_i32_e32 v2, v2, v5
	v_xor_b32_e32 v5, 4, v213
	v_cmp_lt_i32_e32 vcc, v5, v160
	s_nop 1
	v_cndmask_b32_e32 v5, v213, v5, vcc
	v_lshlrev_b32_e32 v5, 2, v5
	ds_bpermute_b32 v5, v5, v2
	s_waitcnt lgkmcnt(0)
	v_max_i32_e32 v2, v2, v5
	v_xor_b32_e32 v5, 8, v213
	v_cmp_lt_i32_e32 vcc, v5, v160
	s_nop 1
	v_cndmask_b32_e32 v5, v213, v5, vcc
	v_lshlrev_b32_e32 v5, 2, v5
	ds_bpermute_b32 v5, v5, v2
	s_waitcnt lgkmcnt(0)
	v_max_i32_e32 v2, v2, v5
	v_xor_b32_e32 v5, 16, v213
	v_cmp_lt_i32_e32 vcc, v5, v160
	s_nop 1
	v_cndmask_b32_e32 v5, v213, v5, vcc
	v_lshlrev_b32_e32 v5, 2, v5
	ds_bpermute_b32 v5, v5, v2
	v_cmp_eq_u32_e32 vcc, 0, v158
	s_and_saveexec_b64 s[12:13], vcc
	s_cbranch_execz .LBB0_353
	s_ashr_i32 s1, s0, 31
	s_lshl_b64 s[0:1], s[0:1], 2
	v_readlane_b32 s14, v252, 26
	v_readlane_b32 s15, v252, 27
	s_add_u32 s0, s14, s0
	s_addc_u32 s1, s15, s1
	s_waitcnt lgkmcnt(0)
	v_max_i32_e32 v2, v2, v5
	global_store_dword v3, v2, s[0:1]
